# weight-conversion stores whose consumers are several phases away (w_out, pool_w, FFN2 gate/up/down) take the nt hint so they do not displace soon-needed data in the memory-side cache
# baseline (speedup 1.0000x reference)
; __device__ __forceinline__ void p0_transpose_item(const float* W, int K, int N, bf16_t* WT, int mode, LAS float* scr, int item, int lane) {
;     const int nblk = N / 32, kb = item / nblk, nb = item % nblk, k0 = 64 * kb, n0 = 32 * nb;
;     float v[32];
;     const float* wp = W + (size_t)(k0 + (lane >> 5)) * N + n0 + (lane & 31);
; #pragma unroll
;     for (int i = 0; i < 32; ++i) v[i] = __builtin_nontemporal_load(wp + (size_t)(2 * i) * N);
; #pragma unroll
;     for (int i = 0; i < 32; ++i) scr[(2 * i + (lane >> 5)) * 33 + (lane & 31)] = v[i];
.LBB0_120:
	s_cmpk_gt_i32 s85, 0x15ff
	s_mov_b64 s[16:17], -1
	s_cbranch_scc0 .LBB0_134
	s_cmpk_gt_u32 s85, 0x21ff
	s_cbranch_scc0 .LBB0_131
	s_cmpk_gt_u32 s85, 0x29ff
	s_cbranch_scc0 .LBB0_128
	s_cmpk_gt_u32 s85, 0x2a7f
	s_cbranch_scc0 .LBB0_125
	s_add_i32 s14, s85, 0xd580
	s_and_b32 s16, s14, 0xffff
	s_load_dwordx2 s[86:87], s[4:5], 0x80
	s_mul_i32 s16, s16, 0xba2f
	s_lshr_b32 s16, s16, 23
	s_mul_i32 s17, s16, 0xb0
	s_sub_i32 s14, s14, s17
	v_lshl_or_b32 v11, s16, 6, v16
	s_and_b32 s17, s14, 0xffff
	v_mul_u32_u24_e32 v12, 0x5800, v11
	v_mov_b32_e32 v13, v1
	s_waitcnt lgkmcnt(0)
	v_lshl_add_u64 v[12:13], s[86:87], 0, v[12:13]
	s_lshl_b32 s14, s17, 7
	v_lshl_add_u64 v[12:13], v[12:13], 0, s[14:15]
	v_lshl_add_u64 v[12:13], v[12:13], 0, v[0:1]
	v_add_co_u32_e32 v32, vcc, s27, v12
	s_mov_b32 s14, 0x16000
	s_nop 0
	v_addc_co_u32_e32 v33, vcc, 0, v13, vcc
	v_add_co_u32_e32 v34, vcc, s14, v12
	s_mov_b32 s14, 0x21000
	s_nop 0
	v_addc_co_u32_e32 v35, vcc, 0, v13, vcc
	v_add_co_u32_e32 v36, vcc, s14, v12
	s_mov_b32 s14, 0x37000
	s_nop 0
	v_addc_co_u32_e32 v37, vcc, 0, v13, vcc
	v_add_co_u32_e32 v38, vcc, s21, v12
	s_lshl_b32 s86, s17, 5
	s_nop 0
	v_addc_co_u32_e32 v39, vcc, 0, v13, vcc
	v_add_co_u32_e32 v40, vcc, s14, v12
	s_mov_b32 s14, 0x4d000
	s_nop 0
	v_addc_co_u32_e32 v41, vcc, 0, v13, vcc
	v_add_co_u32_e32 v42, vcc, s33, v12
	s_nop 1
	v_addc_co_u32_e32 v43, vcc, 0, v13, vcc
	v_add_co_u32_e32 v44, vcc, s14, v12
	s_mov_b32 s14, 0x63000
	s_nop 0
	v_addc_co_u32_e32 v45, vcc, 0, v13, vcc
	global_load_dword v11, v[12:13], off nt
	global_load_dword v31, v[32:33], off nt
	global_load_dword v48, v[34:35], off nt
	global_load_dword v49, v[36:37], off nt
	global_load_dword v50, v[38:39], off nt
	global_load_dword v51, v[40:41], off nt
	global_load_dword v52, v[42:43], off nt
	global_load_dword v53, v[44:45], off nt
	v_add_co_u32_e32 v32, vcc, s34, v12
	s_nop 1
	v_addc_co_u32_e32 v33, vcc, 0, v13, vcc
	v_add_co_u32_e32 v34, vcc, s14, v12
	s_mov_b32 s14, 0x6e000
	s_nop 0
	v_addc_co_u32_e32 v35, vcc, 0, v13, vcc
	v_add_co_u32_e32 v36, vcc, s14, v12
	s_mov_b32 s14, 0x79000
	s_nop 0
	v_addc_co_u32_e32 v37, vcc, 0, v13, vcc
	v_add_co_u32_e32 v38, vcc, s14, v12
	s_mov_b32 s14, 0x8f000
	s_nop 0
	v_addc_co_u32_e32 v39, vcc, 0, v13, vcc
	v_add_co_u32_e32 v40, vcc, s35, v12
	s_nop 1
	v_addc_co_u32_e32 v41, vcc, 0, v13, vcc
	v_add_co_u32_e32 v42, vcc, s14, v12
	s_mov_b32 s14, 0x9a000
	s_nop 0
	v_addc_co_u32_e32 v43, vcc, 0, v13, vcc
	v_add_co_u32_e32 v44, vcc, s14, v12
	s_mov_b32 s14, 0xa5000
	s_nop 0
	v_addc_co_u32_e32 v45, vcc, 0, v13, vcc
	v_add_co_u32_e32 v46, vcc, s14, v12
	s_mov_b32 s14, 0xb0000
	s_nop 0
	v_addc_co_u32_e32 v47, vcc, 0, v13, vcc
	global_load_dword v54, v[32:33], off nt
	global_load_dword v55, v[34:35], off nt
	global_load_dword v56, v[36:37], off nt
	global_load_dword v57, v[38:39], off nt
	global_load_dword v58, v[40:41], off nt
	global_load_dword v59, v[42:43], off nt
	global_load_dword v60, v[44:45], off nt
	global_load_dword v61, v[46:47], off nt
	v_add_co_u32_e32 v32, vcc, s14, v12
	s_mov_b32 s14, 0xbb000
	s_nop 0
	v_addc_co_u32_e32 v33, vcc, 0, v13, vcc
	v_add_co_u32_e32 v34, vcc, s14, v12
	s_mov_b32 s14, 0xc6000
	s_nop 0
	v_addc_co_u32_e32 v35, vcc, 0, v13, vcc
	v_add_co_u32_e32 v36, vcc, s14, v12
	s_mov_b32 s14, 0xd1000
	s_nop 0
	v_addc_co_u32_e32 v37, vcc, 0, v13, vcc
	v_add_co_u32_e32 v38, vcc, s14, v12
	s_mov_b32 s14, 0xdc000
	s_nop 0
	v_addc_co_u32_e32 v39, vcc, 0, v13, vcc
	v_add_co_u32_e32 v40, vcc, s14, v12
	s_mov_b32 s14, 0xe7000
	s_nop 0
	v_addc_co_u32_e32 v41, vcc, 0, v13, vcc
	v_add_co_u32_e32 v42, vcc, s14, v12
	s_mov_b32 s14, 0xf2000
	s_nop 0
	v_addc_co_u32_e32 v43, vcc, 0, v13, vcc
	v_add_co_u32_e32 v44, vcc, s14, v12
	s_mov_b32 s14, 0xfd000
	s_nop 0
	v_addc_co_u32_e32 v45, vcc, 0, v13, vcc
	v_add_co_u32_e32 v46, vcc, s14, v12
	s_mov_b32 s14, 0x108000
	s_nop 0
	v_addc_co_u32_e32 v47, vcc, 0, v13, vcc
	global_load_dword v62, v[32:33], off nt
	global_load_dword v63, v[34:35], off nt
	global_load_dword v64, v[36:37], off nt
	global_load_dword v65, v[38:39], off nt
	global_load_dword v66, v[40:41], off nt
	global_load_dword v67, v[42:43], off nt
	global_load_dword v68, v[44:45], off nt
	s_nop 0
	global_load_dword v46, v[46:47], off nt
	v_add_co_u32_e32 v32, vcc, s14, v12
	s_mov_b32 s14, 0x113000
	s_nop 0
	v_addc_co_u32_e32 v33, vcc, 0, v13, vcc
	v_add_co_u32_e32 v34, vcc, s14, v12
	s_mov_b32 s14, 0x11e000
	s_nop 0
	v_addc_co_u32_e32 v35, vcc, 0, v13, vcc
	v_add_co_u32_e32 v36, vcc, s14, v12
	s_mov_b32 s14, 0x129000
	s_nop 0
	v_addc_co_u32_e32 v37, vcc, 0, v13, vcc
	v_add_co_u32_e32 v38, vcc, s14, v12
	s_mov_b32 s14, 0x134000
	s_nop 0
	v_addc_co_u32_e32 v39, vcc, 0, v13, vcc
	v_add_co_u32_e32 v40, vcc, s14, v12
	s_mov_b32 s14, 0x13f000
	s_nop 0
	v_addc_co_u32_e32 v41, vcc, 0, v13, vcc
	v_add_co_u32_e32 v42, vcc, s14, v12
	s_mov_b32 s14, 0x14a000
	s_nop 0
	v_addc_co_u32_e32 v43, vcc, 0, v13, vcc
	v_add_co_u32_e32 v44, vcc, s14, v12
	s_mov_b32 s14, 0x155000
	s_nop 0
	v_addc_co_u32_e32 v45, vcc, 0, v13, vcc
	v_add_co_u32_e32 v12, vcc, s14, v12
	s_lshl_b32 s14, s17, 6
	s_nop 0
	v_addc_co_u32_e32 v13, vcc, 0, v13, vcc
	global_load_dword v32, v[32:33], off nt
	s_nop 0
	global_load_dword v33, v[34:35], off nt
	s_nop 0
	global_load_dword v34, v[36:37], off nt
	global_load_dword v35, v[38:39], off nt
	s_nop 0
	global_load_dword v36, v[40:41], off nt
	global_load_dword v37, v[42:43], off nt
	global_load_dword v38, v[44:45], off nt
	s_nop 0
	global_load_dword v12, v[12:13], off nt
	s_waitcnt vmcnt(30)
	ds_write2_b32 v17, v11, v31 offset1:66
	s_waitcnt vmcnt(28)
	ds_write2_b32 v17, v48, v49 offset0:132 offset1:198
	s_waitcnt vmcnt(26)
; #define LAS __attribute__((address_space(3)))
; __device__ __forceinline__ unsigned pk2(float lo, float hi) { unsigned r; asm volatile("v_cvt_pk_bf16_f32 %0, %1, %2" : "=v"(r) : "v"(lo), "v"(hi)); return r; }
; __device__ __forceinline__ void p0_transpose_item(const float* W, int K, int N, bf16_t* WT, int mode, LAS float* scr, int item, int lane) {
;     ...
;     for (int i = 0; i < 32; ++i) scr[(2 * i + (lane >> 5)) * 33 + (lane & 31)] = v[i];
;     asm volatile("s_waitcnt lgkmcnt(0)" ::: "memory");
;     const int c = lane & 7;
; #pragma unroll
;     for (int j = 0; j < 4; ++j) { const int n = (lane >> 3) + 8 * j; const LAS float* s = scr + (8 * c) * 33 + n;
;         u32x4 o; o.x = pk2(s[0 * 33], s[1 * 33]); o.y = pk2(s[2 * 33], s[3 * 33]); o.z = pk2(s[4 * 33], s[5 * 33]); o.w = pk2(s[6 * 33], s[7 * 33]);
;         const int nn = n0 + n; const int drow = mode == 0 ? nn : ((nn >> 7) << 8) + (nn & 127) + (mode == 2 ? 128 : 0);
;         *(u32x4*)(WT + (size_t)drow * K + k0 + 8 * c) = o; }
	ds_write2_b32 v24, v50, v51 offset0:8 offset1:74
	s_waitcnt vmcnt(24)
	ds_write2_b32 v24, v52, v53 offset0:140 offset1:206
	s_waitcnt vmcnt(22)
	ds_write2_b32 v25, v54, v55 offset0:16 offset1:82
	s_waitcnt vmcnt(20)
	ds_write2_b32 v25, v56, v57 offset0:148 offset1:214
	s_waitcnt vmcnt(18)
	ds_write2_b32 v26, v58, v59 offset0:24 offset1:90
	s_waitcnt vmcnt(16)
	ds_write2_b32 v26, v60, v61 offset0:156 offset1:222
	s_waitcnt vmcnt(14)
	ds_write2_b32 v27, v62, v63 offset0:32 offset1:98
	s_waitcnt vmcnt(12)
	ds_write2_b32 v27, v64, v65 offset0:164 offset1:230
	s_waitcnt vmcnt(10)
	ds_write2_b32 v28, v66, v67 offset0:40 offset1:106
	s_waitcnt vmcnt(8)
	ds_write2_b32 v28, v68, v46 offset0:172 offset1:238
	s_waitcnt vmcnt(6)
	ds_write2_b32 v29, v32, v33 offset0:48 offset1:114
	s_waitcnt vmcnt(4)
	ds_write2_b32 v29, v34, v35 offset0:180 offset1:246
	s_waitcnt vmcnt(2)
	ds_write2_b32 v30, v36, v37 offset0:56 offset1:122
	s_waitcnt vmcnt(0)
	ds_write2_b32 v30, v38, v12 offset0:188 offset1:254
	s_waitcnt lgkmcnt(0)
	s_and_b32 s17, s14, 0x3f00
	s_lshl_b32 s14, s16, 7
	ds_read2_b32 v[12:13], v19 offset1:33
	v_lshl_add_u64 v[36:37], v[2:3], 0, s[14:15]
	s_and_b32 s14, s86, 0x60
	s_waitcnt lgkmcnt(0)
	v_cvt_pk_bf16_f32 v32, v12, v13
	ds_read2_b32 v[12:13], v19 offset0:66 offset1:99
	v_or_b32_e32 v11, s14, v18
	s_waitcnt lgkmcnt(0)
	v_cvt_pk_bf16_f32 v33, v12, v13
	ds_read2_b32 v[12:13], v19 offset0:132 offset1:165
	v_or_b32_e32 v11, s17, v11
	s_waitcnt lgkmcnt(0)
	v_cvt_pk_bf16_f32 v34, v12, v13
	ds_read2_b32 v[12:13], v19 offset0:198 offset1:231
	v_lshlrev_b32_e32 v38, 12, v11
	v_mov_b32_e32 v39, v1
	s_waitcnt lgkmcnt(0)
	v_cvt_pk_bf16_f32 v35, v12, v13
	ds_read2_b32 v[12:13], v19 offset0:8 offset1:41
	v_lshl_add_u64 v[38:39], v[36:37], 0, v[38:39]
	global_store_dwordx4 v[38:39], v[32:35], off nt
	v_or_b32_e32 v11, s14, v20
	v_or_b32_e32 v11, s17, v11
	s_waitcnt lgkmcnt(0)
	v_cvt_pk_bf16_f32 v32, v12, v13
	ds_read2_b32 v[12:13], v19 offset0:74 offset1:107
	s_waitcnt lgkmcnt(0)
	v_cvt_pk_bf16_f32 v33, v12, v13
	ds_read2_b32 v[12:13], v19 offset0:140 offset1:173
	s_waitcnt lgkmcnt(0)
	v_cvt_pk_bf16_f32 v34, v12, v13
	ds_read2_b32 v[12:13], v19 offset0:206 offset1:239
	v_lshlrev_b32_e32 v38, 12, v11
	v_mov_b32_e32 v39, v1
	s_waitcnt lgkmcnt(0)
	v_cvt_pk_bf16_f32 v35, v12, v13
	ds_read2_b32 v[12:13], v19 offset0:16 offset1:49
	v_lshl_add_u64 v[38:39], v[36:37], 0, v[38:39]
	global_store_dwordx4 v[38:39], v[32:35], off nt
	v_or_b32_e32 v11, s14, v21
	v_or_b32_e32 v11, s17, v11
	s_waitcnt lgkmcnt(0)
	v_cvt_pk_bf16_f32 v32, v12, v13
	ds_read2_b32 v[12:13], v19 offset0:82 offset1:115
	s_waitcnt lgkmcnt(0)
	v_cvt_pk_bf16_f32 v33, v12, v13
	ds_read2_b32 v[12:13], v19 offset0:148 offset1:181
	s_waitcnt lgkmcnt(0)
	v_cvt_pk_bf16_f32 v34, v12, v13
	ds_read2_b32 v[12:13], v19 offset0:214 offset1:247
	v_lshlrev_b32_e32 v38, 12, v11
	v_mov_b32_e32 v39, v1
	s_waitcnt lgkmcnt(0)
	v_cvt_pk_bf16_f32 v35, v12, v13
	ds_read2_b32 v[12:13], v19 offset0:24 offset1:57
	v_lshl_add_u64 v[38:39], v[36:37], 0, v[38:39]
	global_store_dwordx4 v[38:39], v[32:35], off nt
	v_or_b32_e32 v11, s14, v22
	v_or_b32_e32 v11, s17, v11
	s_waitcnt lgkmcnt(0)
	v_cvt_pk_bf16_f32 v32, v12, v13
	ds_read2_b32 v[12:13], v19 offset0:90 offset1:123
	s_waitcnt lgkmcnt(0)
	v_cvt_pk_bf16_f32 v33, v12, v13
	ds_read2_b32 v[12:13], v19 offset0:156 offset1:189
	s_waitcnt lgkmcnt(0)
	v_cvt_pk_bf16_f32 v34, v12, v13
	ds_read2_b32 v[12:13], v19 offset0:222 offset1:255
	s_waitcnt lgkmcnt(0)
	v_cvt_pk_bf16_f32 v35, v12, v13
	v_lshlrev_b32_e32 v12, 12, v11
	v_mov_b32_e32 v13, v1
	v_lshl_add_u64 v[12:13], v[36:37], 0, v[12:13]
	global_store_dwordx4 v[12:13], v[32:35], off nt
	s_waitcnt lgkmcnt(0)
	s_mov_b64 s[16:17], 0
.LBB0_125:
	s_andn2_b64 vcc, exec, s[16:17]
	s_cbranch_vccnz .LBB0_127
	s_load_dwordx2 s[16:17], s[4:5], 0x60
	s_add_i32 s14, s85, 0xffffd600
	s_lshr_b32 s14, s14, 5
	s_lshl_b64 s[86:87], s[14:15], 18
	v_mov_b32_e32 v13, v1
	s_waitcnt lgkmcnt(0)
	s_add_u32 s88, s16, s86
	s_addc_u32 s89, s17, s87
	s_lshl_b64 s[86:87], s[14:15], 17
	s_add_u32 s17, s3, s86
	s_addc_u32 s86, s18, s87
	s_and_b32 s87, s25, 0xc0
	v_or_b32_e32 v11, s87, v16
	s_and_b32 s16, s22, 0xe0
	v_lshlrev_b32_e32 v12, 10, v11
	v_lshl_add_u64 v[12:13], s[88:89], 0, v[12:13]
	s_lshl_b32 s14, s16, 2
	v_lshl_add_u64 v[12:13], v[12:13], 0, s[14:15]
	v_lshl_add_u64 v[12:13], v[12:13], 0, v[0:1]
	s_movk_i32 s14, 0x1000
	v_add_co_u32_e32 v32, vcc, s14, v12
	s_movk_i32 s14, 0x2000
	s_nop 0
	v_addc_co_u32_e32 v33, vcc, 0, v13, vcc
	v_add_co_u32_e32 v34, vcc, s14, v12
	s_movk_i32 s14, 0x3000
	s_nop 0
	v_addc_co_u32_e32 v35, vcc, 0, v13, vcc
	v_add_co_u32_e32 v36, vcc, s14, v12
	s_movk_i32 s14, 0x5000
	s_nop 0
	v_addc_co_u32_e32 v37, vcc, 0, v13, vcc
	v_add_co_u32_e32 v38, vcc, s36, v12
	s_nop 1
	v_addc_co_u32_e32 v39, vcc, 0, v13, vcc
	global_load_dword v11, v[34:35], off offset:-4096 nt
	global_load_dword v31, v[34:35], off nt
	global_load_dword v50, v[34:35], off offset:2048 nt
	global_load_dword v51, v[38:39], off offset:-4096 nt
	global_load_dword v52, v[38:39], off nt
	v_add_co_u32_e32 v34, vcc, s14, v12
	s_movk_i32 s14, 0x7000
	s_nop 0
	v_addc_co_u32_e32 v35, vcc, 0, v13, vcc
	v_add_co_u32_e32 v40, vcc, s37, v12
	s_nop 1
	v_addc_co_u32_e32 v41, vcc, 0, v13, vcc
	v_add_co_u32_e32 v42, vcc, s14, v12
	s_mov_b32 s14, 0x9000
	s_nop 0
	v_addc_co_u32_e32 v43, vcc, 0, v13, vcc
	v_add_co_u32_e32 v44, vcc, s38, v12
	s_nop 1
	v_addc_co_u32_e32 v45, vcc, 0, v13, vcc
	v_add_co_u32_e32 v46, vcc, s14, v12
	s_mov_b32 s14, 0xa000
	s_nop 0
	v_addc_co_u32_e32 v47, vcc, 0, v13, vcc
	v_add_co_u32_e32 v48, vcc, s14, v12
	s_mov_b32 s14, 0xd000
; #define LAS __attribute__((address_space(3)))
; __device__ __forceinline__ unsigned pk2(float lo, float hi) { unsigned r; asm volatile("v_cvt_pk_bf16_f32 %0, %1, %2" : "=v"(r) : "v"(lo), "v"(hi)); return r; }
; __device__ __forceinline__ void p0_transpose_item(const float* W, int K, int N, bf16_t* WT, int mode, LAS float* scr, int item, int lane) {
;     ...
;     const float* wp = W + (size_t)(k0 + (lane >> 5)) * N + n0 + (lane & 31);
; #pragma unroll
;     for (int i = 0; i < 32; ++i) v[i] = __builtin_nontemporal_load(wp + (size_t)(2 * i) * N);
; #pragma unroll
;     for (int i = 0; i < 32; ++i) scr[(2 * i + (lane >> 5)) * 33 + (lane & 31)] = v[i];
;     asm volatile("s_waitcnt lgkmcnt(0)" ::: "memory");
;     const int c = lane & 7;
; #pragma unroll
;     for (int j = 0; j < 4; ++j) { const int n = (lane >> 3) + 8 * j; const LAS float* s = scr + (8 * c) * 33 + n;
;         u32x4 o; o.x = pk2(s[0 * 33], s[1 * 33]); o.y = pk2(s[2 * 33], s[3 * 33]); o.z = pk2(s[4 * 33], s[5 * 33]); o.w = pk2(s[6 * 33], s[7 * 33]);
;         const int nn = n0 + n; const int drow = mode == 0 ? nn : ((nn >> 7) << 8) + (nn & 127) + (mode == 2 ? 128 : 0);
;         *(u32x4*)(WT + (size_t)drow * K + k0 + 8 * c) = o; }
	s_nop 0
	v_addc_co_u32_e32 v49, vcc, 0, v13, vcc
	global_load_dword v53, v[38:39], off offset:2048 nt
	global_load_dword v54, v[40:41], off offset:-4096 nt
	global_load_dword v55, v[40:41], off nt
	global_load_dword v56, v[40:41], off offset:2048 nt
	global_load_dword v57, v[44:45], off offset:-4096 nt
	global_load_dword v58, v[44:45], off nt
	s_nop 0
	global_load_dword v44, v[44:45], off offset:2048 nt
	s_nop 0
	global_load_dword v45, v[48:49], off offset:-4096 nt
	v_add_co_u32_e32 v38, vcc, s27, v12
	s_nop 1
	v_addc_co_u32_e32 v39, vcc, 0, v13, vcc
	v_add_co_u32_e32 v40, vcc, s39, v12
	global_load_dword v59, v[12:13], off nt
	global_load_dword v60, v[12:13], off offset:2048 nt
	global_load_dword v61, v[32:33], off offset:2048 nt
	s_nop 0
	global_load_dword v36, v[36:37], off offset:2048 nt
	s_nop 0
	global_load_dword v37, v[34:35], off offset:2048 nt
	s_nop 0
	global_load_dword v42, v[42:43], off offset:2048 nt
	s_nop 0
	global_load_dword v43, v[46:47], off offset:2048 nt
	s_nop 0
	global_load_dword v38, v[38:39], off offset:2048 nt
	v_addc_co_u32_e32 v41, vcc, 0, v13, vcc
	v_add_co_u32_e32 v32, vcc, s14, v12
	s_mov_b32 s14, 0xe000
	s_nop 0
	v_addc_co_u32_e32 v33, vcc, 0, v13, vcc
	v_add_co_u32_e32 v34, vcc, s14, v12
	s_lshl_b32 s14, s87, 1
	s_nop 0
	v_addc_co_u32_e32 v35, vcc, 0, v13, vcc
	v_add_co_u32_e32 v12, vcc, s40, v12
	global_load_dword v39, v[48:49], off nt
	global_load_dword v46, v[48:49], off offset:2048 nt
	global_load_dword v47, v[40:41], off offset:-4096 nt
	s_nop 0
	global_load_dword v48, v[40:41], off nt
	s_nop 0
	global_load_dword v40, v[40:41], off offset:2048 nt
	s_nop 0
	global_load_dword v41, v[34:35], off offset:-4096 nt
	global_load_dword v49, v[34:35], off nt
	s_nop 0
	global_load_dword v34, v[34:35], off offset:2048 nt
	v_addc_co_u32_e32 v13, vcc, 0, v13, vcc
	global_load_dword v32, v[32:33], off offset:2048 nt
	s_nop 0
	global_load_dword v33, v[12:13], off nt
	s_nop 0
	global_load_dword v12, v[12:13], off offset:2048 nt
	s_add_u32 s88, s17, s14
	s_addc_u32 s89, s86, 0
	s_waitcnt vmcnt(17)
	ds_write2_b32 v17, v59, v60 offset1:66
	s_waitcnt vmcnt(16)
	ds_write2_b32 v17, v11, v61 offset0:132 offset1:198
	ds_write2_b32 v24, v31, v50 offset0:8 offset1:74
	s_waitcnt vmcnt(15)
	ds_write2_b32 v24, v51, v36 offset0:140 offset1:206
	ds_write2_b32 v25, v52, v53 offset0:16 offset1:82
	s_waitcnt vmcnt(14)
	ds_write2_b32 v25, v54, v37 offset0:148 offset1:214
	ds_write2_b32 v26, v55, v56 offset0:24 offset1:90
	s_waitcnt vmcnt(13)
	ds_write2_b32 v26, v57, v42 offset0:156 offset1:222
	ds_write2_b32 v27, v58, v44 offset0:32 offset1:98
	s_waitcnt vmcnt(12)
	ds_write2_b32 v27, v45, v43 offset0:164 offset1:230
	s_waitcnt vmcnt(9)
	ds_write2_b32 v28, v39, v46 offset0:40 offset1:106
	s_waitcnt vmcnt(8)
	ds_write2_b32 v28, v47, v38 offset0:172 offset1:238
	s_waitcnt vmcnt(6)
	ds_write2_b32 v29, v48, v40 offset0:48 offset1:114
	s_waitcnt vmcnt(2)
	ds_write2_b32 v29, v41, v32 offset0:180 offset1:246
	ds_write2_b32 v30, v49, v34 offset0:56 offset1:122
	s_waitcnt vmcnt(0)
	ds_write2_b32 v30, v33, v12 offset0:188 offset1:254
	s_waitcnt lgkmcnt(0)
	ds_read2_b32 v[12:13], v19 offset1:33
	s_waitcnt lgkmcnt(0)
	v_cvt_pk_bf16_f32 v32, v12, v13
	ds_read2_b32 v[12:13], v19 offset0:66 offset1:99
	v_mov_b32_e32 v11, v1
	s_waitcnt lgkmcnt(0)
	v_cvt_pk_bf16_f32 v33, v12, v13
	ds_read2_b32 v[12:13], v19 offset0:132 offset1:165
	v_lshl_add_u64 v[36:37], s[88:89], 0, v[10:11]
	v_or_b32_e32 v11, s16, v18
	s_waitcnt lgkmcnt(0)
	v_cvt_pk_bf16_f32 v34, v12, v13
	ds_read2_b32 v[12:13], v19 offset0:198 offset1:231
	v_lshlrev_b32_e32 v38, 9, v11
	v_mov_b32_e32 v39, v1
	s_waitcnt lgkmcnt(0)
	v_cvt_pk_bf16_f32 v35, v12, v13
	ds_read2_b32 v[12:13], v19 offset0:8 offset1:41
	v_lshl_add_u64 v[38:39], v[36:37], 0, v[38:39]
	global_store_dwordx4 v[38:39], v[32:35], off nt
	v_or_b32_e32 v11, s16, v20
	v_lshlrev_b32_e32 v38, 9, v11
	s_waitcnt lgkmcnt(0)
	v_cvt_pk_bf16_f32 v32, v12, v13
	ds_read2_b32 v[12:13], v19 offset0:74 offset1:107
	s_waitcnt lgkmcnt(0)
	v_cvt_pk_bf16_f32 v33, v12, v13
	ds_read2_b32 v[12:13], v19 offset0:140 offset1:173
	s_waitcnt lgkmcnt(0)
	v_cvt_pk_bf16_f32 v34, v12, v13
	ds_read2_b32 v[12:13], v19 offset0:206 offset1:239
	v_mov_b32_e32 v39, v1
	s_waitcnt lgkmcnt(0)
	v_cvt_pk_bf16_f32 v35, v12, v13
	ds_read2_b32 v[12:13], v19 offset0:16 offset1:49
	v_lshl_add_u64 v[38:39], v[36:37], 0, v[38:39]
	global_store_dwordx4 v[38:39], v[32:35], off nt
	v_or_b32_e32 v11, s16, v21
	v_lshlrev_b32_e32 v38, 9, v11
	s_waitcnt lgkmcnt(0)
	v_cvt_pk_bf16_f32 v32, v12, v13
	ds_read2_b32 v[12:13], v19 offset0:82 offset1:115
	s_waitcnt lgkmcnt(0)
	v_cvt_pk_bf16_f32 v33, v12, v13
	ds_read2_b32 v[12:13], v19 offset0:148 offset1:181
	s_waitcnt lgkmcnt(0)
	v_cvt_pk_bf16_f32 v34, v12, v13
	ds_read2_b32 v[12:13], v19 offset0:214 offset1:247
	v_mov_b32_e32 v39, v1
	s_waitcnt lgkmcnt(0)
	v_cvt_pk_bf16_f32 v35, v12, v13
	ds_read2_b32 v[12:13], v19 offset0:24 offset1:57
	v_lshl_add_u64 v[38:39], v[36:37], 0, v[38:39]
	global_store_dwordx4 v[38:39], v[32:35], off nt
	v_or_b32_e32 v11, s16, v22
	s_waitcnt lgkmcnt(0)
	v_cvt_pk_bf16_f32 v32, v12, v13
	ds_read2_b32 v[12:13], v19 offset0:90 offset1:123
	s_waitcnt lgkmcnt(0)
	v_cvt_pk_bf16_f32 v33, v12, v13
	ds_read2_b32 v[12:13], v19 offset0:156 offset1:189
	s_waitcnt lgkmcnt(0)
	v_cvt_pk_bf16_f32 v34, v12, v13
	ds_read2_b32 v[12:13], v19 offset0:222 offset1:255
	s_waitcnt lgkmcnt(0)
	v_cvt_pk_bf16_f32 v35, v12, v13
	v_lshlrev_b32_e32 v12, 9, v11
	v_mov_b32_e32 v13, v1
	v_lshl_add_u64 v[12:13], v[36:37], 0, v[12:13]
	global_store_dwordx4 v[12:13], v[32:35], off nt
	s_waitcnt lgkmcnt(0)

; #define LAS __attribute__((address_space(3)))
; __device__ __forceinline__ void p0_transpose_item(const float* W, int K, int N, bf16_t* WT, int mode, LAS float* scr, int item, int lane) {
;     const int nblk = N / 32, kb = item / nblk, nb = item % nblk, k0 = 64 * kb, n0 = 32 * nb;
;     float v[32];
;     const float* wp = W + (size_t)(k0 + (lane >> 5)) * N + n0 + (lane & 31);
; #pragma unroll
;     for (int i = 0; i < 32; ++i) v[i] = __builtin_nontemporal_load(wp + (size_t)(2 * i) * N);
.LBB0_128:
	s_andn2_b64 vcc, exec, s[16:17]
	s_cbranch_vccnz .LBB0_130
	s_load_dwordx2 s[86:87], s[4:5], 0x70
	s_add_i32 s14, s85, 0xde00
	s_and_b32 s17, s14, 0xffc0
	v_or_b32_e32 v11, s17, v16
	s_and_b32 s16, s22, 0x7e0
	v_lshlrev_b32_e32 v12, 13, v11
	v_mov_b32_e32 v13, v1
	s_waitcnt lgkmcnt(0)
	v_lshl_add_u64 v[12:13], s[86:87], 0, v[12:13]
	s_lshl_b32 s14, s16, 2
	v_lshl_add_u64 v[12:13], v[12:13], 0, s[14:15]
	v_lshl_add_u64 v[12:13], v[12:13], 0, v[0:1]
	v_add_co_u32_e32 v32, vcc, s36, v12
	s_lshl_b32 s14, s17, 1
	s_nop 0
	v_addc_co_u32_e32 v33, vcc, 0, v13, vcc
	v_add_co_u32_e32 v34, vcc, s38, v12
	s_nop 1
	v_addc_co_u32_e32 v35, vcc, 0, v13, vcc
	v_add_co_u32_e32 v36, vcc, s39, v12
	s_nop 1
	v_addc_co_u32_e32 v37, vcc, 0, v13, vcc
	v_add_co_u32_e32 v38, vcc, s41, v12
	s_nop 1
	v_addc_co_u32_e32 v39, vcc, 0, v13, vcc
	v_add_co_u32_e32 v40, vcc, s42, v12
	s_nop 1
	v_addc_co_u32_e32 v41, vcc, 0, v13, vcc
	v_add_co_u32_e32 v42, vcc, s43, v12
	s_nop 1
	v_addc_co_u32_e32 v43, vcc, 0, v13, vcc
	v_add_co_u32_e32 v44, vcc, s44, v12
	s_nop 1
	v_addc_co_u32_e32 v45, vcc, 0, v13, vcc
	global_load_dword v11, v[12:13], off nt
	global_load_dword v31, v[32:33], off nt
	global_load_dword v48, v[34:35], off nt
	global_load_dword v49, v[36:37], off nt
	global_load_dword v50, v[38:39], off nt
	global_load_dword v51, v[40:41], off nt
	global_load_dword v52, v[42:43], off nt
	global_load_dword v53, v[44:45], off nt
	v_add_co_u32_e32 v32, vcc, s45, v12
	s_nop 1
	v_addc_co_u32_e32 v33, vcc, 0, v13, vcc
	v_add_co_u32_e32 v34, vcc, s46, v12
	s_nop 1
	v_addc_co_u32_e32 v35, vcc, 0, v13, vcc
	v_add_co_u32_e32 v36, vcc, s47, v12
	s_nop 1
	v_addc_co_u32_e32 v37, vcc, 0, v13, vcc
	v_add_co_u32_e32 v38, vcc, s21, v12
	s_nop 1
	v_addc_co_u32_e32 v39, vcc, 0, v13, vcc
	v_add_co_u32_e32 v40, vcc, s48, v12
	s_nop 1
	v_addc_co_u32_e32 v41, vcc, 0, v13, vcc
	v_add_co_u32_e32 v42, vcc, s49, v12
	s_nop 1
	v_addc_co_u32_e32 v43, vcc, 0, v13, vcc
	v_add_co_u32_e32 v44, vcc, s50, v12
	s_nop 1
	v_addc_co_u32_e32 v45, vcc, 0, v13, vcc
	v_add_co_u32_e32 v46, vcc, s51, v12
	s_nop 1
	v_addc_co_u32_e32 v47, vcc, 0, v13, vcc
	global_load_dword v54, v[32:33], off nt
	global_load_dword v55, v[34:35], off nt
	global_load_dword v56, v[36:37], off nt
	global_load_dword v57, v[38:39], off nt
	global_load_dword v58, v[40:41], off nt
	global_load_dword v59, v[42:43], off nt
	global_load_dword v60, v[44:45], off nt
	global_load_dword v61, v[46:47], off nt
	v_add_co_u32_e32 v32, vcc, s52, v12
	s_nop 1
	v_addc_co_u32_e32 v33, vcc, 0, v13, vcc
	v_add_co_u32_e32 v34, vcc, s53, v12
	s_nop 1
	v_addc_co_u32_e32 v35, vcc, 0, v13, vcc
	v_add_co_u32_e32 v36, vcc, s54, v12
	s_nop 1
	v_addc_co_u32_e32 v37, vcc, 0, v13, vcc
	v_add_co_u32_e32 v38, vcc, s55, v12
	s_nop 1
	v_addc_co_u32_e32 v39, vcc, 0, v13, vcc
	v_add_co_u32_e32 v40, vcc, s56, v12
	s_nop 1
	v_addc_co_u32_e32 v41, vcc, 0, v13, vcc
	v_add_co_u32_e32 v42, vcc, s57, v12
	s_nop 1
	v_addc_co_u32_e32 v43, vcc, 0, v13, vcc
	v_add_co_u32_e32 v44, vcc, s34, v12
	s_nop 1
	v_addc_co_u32_e32 v45, vcc, 0, v13, vcc
	v_add_co_u32_e32 v46, vcc, s58, v12
	s_nop 1
	v_addc_co_u32_e32 v47, vcc, 0, v13, vcc
	global_load_dword v62, v[32:33], off nt
	global_load_dword v63, v[34:35], off nt
	global_load_dword v64, v[36:37], off nt
	global_load_dword v65, v[38:39], off nt
	global_load_dword v66, v[40:41], off nt
	global_load_dword v67, v[42:43], off nt
	global_load_dword v68, v[44:45], off nt
	s_nop 0
	global_load_dword v46, v[46:47], off nt
	v_add_co_u32_e32 v32, vcc, s59, v12
	s_nop 1
	v_addc_co_u32_e32 v33, vcc, 0, v13, vcc
	v_add_co_u32_e32 v34, vcc, s60, v12
	s_nop 1
	v_addc_co_u32_e32 v35, vcc, 0, v13, vcc
	v_add_co_u32_e32 v36, vcc, s61, v12
	s_nop 1
	v_addc_co_u32_e32 v37, vcc, 0, v13, vcc
	v_add_co_u32_e32 v38, vcc, s62, v12
	s_nop 1
	v_addc_co_u32_e32 v39, vcc, 0, v13, vcc
	v_add_co_u32_e32 v40, vcc, s63, v12
	s_nop 1
	v_addc_co_u32_e32 v41, vcc, 0, v13, vcc
	v_add_co_u32_e32 v42, vcc, s64, v12
	s_nop 1
	v_addc_co_u32_e32 v43, vcc, 0, v13, vcc
	v_add_co_u32_e32 v44, vcc, s65, v12
	s_nop 1
	v_addc_co_u32_e32 v45, vcc, 0, v13, vcc
	v_add_co_u32_e32 v12, vcc, s66, v12
	s_nop 1
	v_addc_co_u32_e32 v13, vcc, 0, v13, vcc
	global_load_dword v32, v[32:33], off nt
	s_nop 0
	global_load_dword v33, v[34:35], off nt
	s_nop 0
	global_load_dword v34, v[36:37], off nt
	global_load_dword v35, v[38:39], off nt
	s_nop 0
	global_load_dword v36, v[40:41], off nt
	global_load_dword v37, v[42:43], off nt
	global_load_dword v38, v[44:45], off nt
	s_nop 0
	global_load_dword v12, v[12:13], off nt
	s_waitcnt vmcnt(30)
; #define LAS __attribute__((address_space(3)))
; __device__ __forceinline__ unsigned pk2(float lo, float hi) { unsigned r; asm volatile("v_cvt_pk_bf16_f32 %0, %1, %2" : "=v"(r) : "v"(lo), "v"(hi)); return r; }
; __device__ __forceinline__ void p0_transpose_item(const float* W, int K, int N, bf16_t* WT, int mode, LAS float* scr, int item, int lane) {
;     ...
;     for (int i = 0; i < 32; ++i) scr[(2 * i + (lane >> 5)) * 33 + (lane & 31)] = v[i];
;     asm volatile("s_waitcnt lgkmcnt(0)" ::: "memory");
;     const int c = lane & 7;
; #pragma unroll
;     for (int j = 0; j < 4; ++j) { const int n = (lane >> 3) + 8 * j; const LAS float* s = scr + (8 * c) * 33 + n;
;         u32x4 o; o.x = pk2(s[0 * 33], s[1 * 33]); o.y = pk2(s[2 * 33], s[3 * 33]); o.z = pk2(s[4 * 33], s[5 * 33]); o.w = pk2(s[6 * 33], s[7 * 33]);
;         const int nn = n0 + n; const int drow = mode == 0 ? nn : ((nn >> 7) << 8) + (nn & 127) + (mode == 2 ? 128 : 0);
;         *(u32x4*)(WT + (size_t)drow * K + k0 + 8 * c) = o; }
	ds_write2_b32 v17, v11, v31 offset1:66
	s_waitcnt vmcnt(28)
	ds_write2_b32 v17, v48, v49 offset0:132 offset1:198
	s_waitcnt vmcnt(26)
	ds_write2_b32 v24, v50, v51 offset0:8 offset1:74
	s_waitcnt vmcnt(24)
	ds_write2_b32 v24, v52, v53 offset0:140 offset1:206
	s_waitcnt vmcnt(22)
	ds_write2_b32 v25, v54, v55 offset0:16 offset1:82
	s_waitcnt vmcnt(20)
	ds_write2_b32 v25, v56, v57 offset0:148 offset1:214
	s_waitcnt vmcnt(18)
	ds_write2_b32 v26, v58, v59 offset0:24 offset1:90
	s_waitcnt vmcnt(16)
	ds_write2_b32 v26, v60, v61 offset0:156 offset1:222
	s_waitcnt vmcnt(14)
	ds_write2_b32 v27, v62, v63 offset0:32 offset1:98
	s_waitcnt vmcnt(12)
	ds_write2_b32 v27, v64, v65 offset0:164 offset1:230
	s_waitcnt vmcnt(10)
	ds_write2_b32 v28, v66, v67 offset0:40 offset1:106
	s_waitcnt vmcnt(8)
	ds_write2_b32 v28, v68, v46 offset0:172 offset1:238
	s_waitcnt vmcnt(6)
	ds_write2_b32 v29, v32, v33 offset0:48 offset1:114
	s_waitcnt vmcnt(4)
	ds_write2_b32 v29, v34, v35 offset0:180 offset1:246
	s_waitcnt vmcnt(2)
	ds_write2_b32 v30, v36, v37 offset0:56 offset1:122
	s_waitcnt vmcnt(0)
	ds_write2_b32 v30, v38, v12 offset0:188 offset1:254
	s_waitcnt lgkmcnt(0)
	ds_read2_b32 v[12:13], v19 offset1:33
	s_waitcnt lgkmcnt(0)
	v_cvt_pk_bf16_f32 v32, v12, v13
	ds_read2_b32 v[12:13], v19 offset0:66 offset1:99
	s_waitcnt lgkmcnt(0)
	v_cvt_pk_bf16_f32 v33, v12, v13
	ds_read2_b32 v[12:13], v19 offset0:132 offset1:165
	v_or_b32_e32 v11, s16, v18
	s_waitcnt lgkmcnt(0)
	v_cvt_pk_bf16_f32 v34, v12, v13
	ds_read2_b32 v[12:13], v19 offset0:198 offset1:231
	v_lshl_add_u64 v[36:37], v[4:5], 0, s[14:15]
	v_lshlrev_b32_e32 v38, 12, v11
	v_mov_b32_e32 v39, v1
	s_waitcnt lgkmcnt(0)
	v_cvt_pk_bf16_f32 v35, v12, v13
	ds_read2_b32 v[12:13], v19 offset0:8 offset1:41
	v_lshl_add_u64 v[38:39], v[36:37], 0, v[38:39]
	global_store_dwordx4 v[38:39], v[32:35], off nt
	v_or_b32_e32 v11, s16, v20
	v_lshlrev_b32_e32 v38, 12, v11
	s_waitcnt lgkmcnt(0)
	v_cvt_pk_bf16_f32 v32, v12, v13
	ds_read2_b32 v[12:13], v19 offset0:74 offset1:107
	s_waitcnt lgkmcnt(0)
	v_cvt_pk_bf16_f32 v33, v12, v13
	ds_read2_b32 v[12:13], v19 offset0:140 offset1:173
	s_waitcnt lgkmcnt(0)
	v_cvt_pk_bf16_f32 v34, v12, v13
	ds_read2_b32 v[12:13], v19 offset0:206 offset1:239
	v_mov_b32_e32 v39, v1
	s_waitcnt lgkmcnt(0)
	v_cvt_pk_bf16_f32 v35, v12, v13
	ds_read2_b32 v[12:13], v19 offset0:16 offset1:49
	v_lshl_add_u64 v[38:39], v[36:37], 0, v[38:39]
	global_store_dwordx4 v[38:39], v[32:35], off nt
	v_or_b32_e32 v11, s16, v21
	v_lshlrev_b32_e32 v38, 12, v11
	s_waitcnt lgkmcnt(0)
	v_cvt_pk_bf16_f32 v32, v12, v13
	ds_read2_b32 v[12:13], v19 offset0:82 offset1:115
	s_waitcnt lgkmcnt(0)
	v_cvt_pk_bf16_f32 v33, v12, v13
	ds_read2_b32 v[12:13], v19 offset0:148 offset1:181
	s_waitcnt lgkmcnt(0)
	v_cvt_pk_bf16_f32 v34, v12, v13
	ds_read2_b32 v[12:13], v19 offset0:214 offset1:247
	v_mov_b32_e32 v39, v1
	s_waitcnt lgkmcnt(0)
	v_cvt_pk_bf16_f32 v35, v12, v13
	ds_read2_b32 v[12:13], v19 offset0:24 offset1:57
	v_lshl_add_u64 v[38:39], v[36:37], 0, v[38:39]
	global_store_dwordx4 v[38:39], v[32:35], off nt
	v_or_b32_e32 v11, s16, v22
	s_waitcnt lgkmcnt(0)
	v_cvt_pk_bf16_f32 v32, v12, v13
	ds_read2_b32 v[12:13], v19 offset0:90 offset1:123
	s_waitcnt lgkmcnt(0)
	v_cvt_pk_bf16_f32 v33, v12, v13
	ds_read2_b32 v[12:13], v19 offset0:156 offset1:189
	s_waitcnt lgkmcnt(0)
	v_cvt_pk_bf16_f32 v34, v12, v13
	ds_read2_b32 v[12:13], v19 offset0:222 offset1:255
	s_waitcnt lgkmcnt(0)
	v_cvt_pk_bf16_f32 v35, v12, v13
	v_lshlrev_b32_e32 v12, 12, v11
	v_mov_b32_e32 v13, v1
	v_lshl_add_u64 v[12:13], v[36:37], 0, v[12:13]
	global_store_dwordx4 v[12:13], v[32:35], off nt
	s_waitcnt lgkmcnt(0)

; #define LAS __attribute__((address_space(3)))
; __device__ __forceinline__ void p0_transpose_item(const float* W, int K, int N, bf16_t* WT, int mode, LAS float* scr, int item, int lane) {
;     const int nblk = N / 32, kb = item / nblk, nb = item % nblk, k0 = 64 * kb, n0 = 32 * nb;
;     float v[32];
;     const float* wp = W + (size_t)(k0 + (lane >> 5)) * N + n0 + (lane & 31);
; #pragma unroll
;     for (int i = 0; i < 32; ++i) v[i] = __builtin_nontemporal_load(wp + (size_t)(2 * i) * N);
.LBB0_141:
	s_cmpk_gt_i32 s14, 0x15ff
	s_mov_b64 s[8:9], -1
	s_cbranch_scc0 .LBB0_155
	s_cmpk_gt_u32 s14, 0x21ff
	s_cbranch_scc0 .LBB0_152
	s_cmpk_gt_u32 s14, 0x29ff
	s_cbranch_scc0 .LBB0_149
	s_cmpk_gt_u32 s14, 0x2a7f
	s_cbranch_scc0 .LBB0_146
	s_add_i32 s6, s14, 0xd580
	s_and_b32 s8, s6, 0xffff
	s_load_dwordx2 s[86:87], s[4:5], 0x80
	s_mul_i32 s8, s8, 0xba2f
	s_lshr_b32 s8, s8, 23
	s_mul_i32 s9, s8, 0xb0
	s_sub_i32 s6, s6, s9
	v_lshl_or_b32 v11, s8, 6, v16
	s_and_b32 s9, s6, 0xffff
	v_mul_u32_u24_e32 v12, 0x5800, v11
	v_mov_b32_e32 v13, v1
	s_waitcnt lgkmcnt(0)
	v_lshl_add_u64 v[12:13], s[86:87], 0, v[12:13]
	s_lshl_b32 s6, s9, 7
	v_lshl_add_u64 v[12:13], v[12:13], 0, s[6:7]
	v_lshl_add_u64 v[12:13], v[12:13], 0, v[0:1]
	v_add_co_u32_e32 v30, vcc, s13, v12
	s_mov_b32 s6, 0x16000
	s_nop 0
	v_addc_co_u32_e32 v31, vcc, 0, v13, vcc
	v_add_co_u32_e32 v32, vcc, s6, v12
	s_mov_b32 s6, 0x21000
	s_nop 0
	v_addc_co_u32_e32 v33, vcc, 0, v13, vcc
	v_add_co_u32_e32 v34, vcc, s6, v12
	s_mov_b32 s6, 0x37000
	s_nop 0
	v_addc_co_u32_e32 v35, vcc, 0, v13, vcc
	v_add_co_u32_e32 v36, vcc, s10, v12
	s_lshl_b32 s86, s9, 5
	s_nop 0
	v_addc_co_u32_e32 v37, vcc, 0, v13, vcc
	v_add_co_u32_e32 v38, vcc, s6, v12
	s_mov_b32 s6, 0x4d000
	s_nop 0
	v_addc_co_u32_e32 v39, vcc, 0, v13, vcc
	v_add_co_u32_e32 v40, vcc, s15, v12
	s_nop 1
	v_addc_co_u32_e32 v41, vcc, 0, v13, vcc
	v_add_co_u32_e32 v42, vcc, s6, v12
	s_mov_b32 s6, 0x63000
	s_nop 0
	v_addc_co_u32_e32 v43, vcc, 0, v13, vcc
	global_load_dword v11, v[12:13], off nt
	global_load_dword v29, v[30:31], off nt
	global_load_dword v46, v[32:33], off nt
	global_load_dword v47, v[34:35], off nt
	global_load_dword v48, v[36:37], off nt
	global_load_dword v49, v[38:39], off nt
	global_load_dword v50, v[40:41], off nt
	global_load_dword v51, v[42:43], off nt
	v_add_co_u32_e32 v30, vcc, s16, v12
	s_nop 1
	v_addc_co_u32_e32 v31, vcc, 0, v13, vcc
	v_add_co_u32_e32 v32, vcc, s6, v12
	s_mov_b32 s6, 0x6e000
	s_nop 0
	v_addc_co_u32_e32 v33, vcc, 0, v13, vcc
	v_add_co_u32_e32 v34, vcc, s6, v12
	s_mov_b32 s6, 0x79000
	s_nop 0
	v_addc_co_u32_e32 v35, vcc, 0, v13, vcc
	v_add_co_u32_e32 v36, vcc, s6, v12
	s_mov_b32 s6, 0x8f000
	s_nop 0
	v_addc_co_u32_e32 v37, vcc, 0, v13, vcc
	v_add_co_u32_e32 v38, vcc, s17, v12
	s_nop 1
	v_addc_co_u32_e32 v39, vcc, 0, v13, vcc
	v_add_co_u32_e32 v40, vcc, s6, v12
	s_mov_b32 s6, 0x9a000
	s_nop 0
	v_addc_co_u32_e32 v41, vcc, 0, v13, vcc
	v_add_co_u32_e32 v42, vcc, s6, v12
	s_mov_b32 s6, 0xa5000
	s_nop 0
	v_addc_co_u32_e32 v43, vcc, 0, v13, vcc
	v_add_co_u32_e32 v44, vcc, s6, v12
	s_mov_b32 s6, 0xb0000
	s_nop 0
	v_addc_co_u32_e32 v45, vcc, 0, v13, vcc
	global_load_dword v52, v[30:31], off nt
	global_load_dword v53, v[32:33], off nt
	global_load_dword v54, v[34:35], off nt
	global_load_dword v55, v[36:37], off nt
	global_load_dword v56, v[38:39], off nt
	global_load_dword v57, v[40:41], off nt
	global_load_dword v58, v[42:43], off nt
	global_load_dword v59, v[44:45], off nt
	v_add_co_u32_e32 v30, vcc, s6, v12
	s_mov_b32 s6, 0xbb000
	s_nop 0
	v_addc_co_u32_e32 v31, vcc, 0, v13, vcc
	v_add_co_u32_e32 v32, vcc, s6, v12
	s_mov_b32 s6, 0xc6000
	s_nop 0
	v_addc_co_u32_e32 v33, vcc, 0, v13, vcc
	v_add_co_u32_e32 v34, vcc, s6, v12
	s_mov_b32 s6, 0xd1000
	s_nop 0
	v_addc_co_u32_e32 v35, vcc, 0, v13, vcc
	v_add_co_u32_e32 v36, vcc, s6, v12
	s_mov_b32 s6, 0xdc000
	s_nop 0
	v_addc_co_u32_e32 v37, vcc, 0, v13, vcc
	v_add_co_u32_e32 v38, vcc, s6, v12
	s_mov_b32 s6, 0xe7000
	s_nop 0
	v_addc_co_u32_e32 v39, vcc, 0, v13, vcc
	v_add_co_u32_e32 v40, vcc, s6, v12
	s_mov_b32 s6, 0xf2000
	s_nop 0
	v_addc_co_u32_e32 v41, vcc, 0, v13, vcc
	v_add_co_u32_e32 v42, vcc, s6, v12
	s_mov_b32 s6, 0xfd000
	s_nop 0
	v_addc_co_u32_e32 v43, vcc, 0, v13, vcc
	v_add_co_u32_e32 v44, vcc, s6, v12
	s_mov_b32 s6, 0x108000
	s_nop 0
	v_addc_co_u32_e32 v45, vcc, 0, v13, vcc
	global_load_dword v60, v[30:31], off nt
	global_load_dword v61, v[32:33], off nt
	global_load_dword v62, v[34:35], off nt
	global_load_dword v63, v[36:37], off nt
	global_load_dword v64, v[38:39], off nt
	global_load_dword v65, v[40:41], off nt
	global_load_dword v66, v[42:43], off nt
	s_nop 0
	global_load_dword v44, v[44:45], off nt
	v_add_co_u32_e32 v30, vcc, s6, v12
	s_mov_b32 s6, 0x113000
	s_nop 0
	v_addc_co_u32_e32 v31, vcc, 0, v13, vcc
	v_add_co_u32_e32 v32, vcc, s6, v12
	s_mov_b32 s6, 0x11e000
	s_nop 0
	v_addc_co_u32_e32 v33, vcc, 0, v13, vcc
	v_add_co_u32_e32 v34, vcc, s6, v12
	s_mov_b32 s6, 0x129000
	s_nop 0
	v_addc_co_u32_e32 v35, vcc, 0, v13, vcc
	v_add_co_u32_e32 v36, vcc, s6, v12
	s_mov_b32 s6, 0x134000
	s_nop 0
	v_addc_co_u32_e32 v37, vcc, 0, v13, vcc
	v_add_co_u32_e32 v38, vcc, s6, v12
	s_lshl_b32 s6, s9, 6
	s_nop 0
	v_addc_co_u32_e32 v39, vcc, 0, v13, vcc
	v_add_co_u32_e32 v40, vcc, s19, v12
	s_and_b32 s9, s6, 0x3f00
	s_nop 0
	v_addc_co_u32_e32 v41, vcc, 0, v13, vcc
	v_add_co_u32_e32 v42, vcc, s20, v12
	s_lshl_b32 s6, s8, 7
	s_nop 0
	v_addc_co_u32_e32 v43, vcc, 0, v13, vcc
	v_add_co_u32_e32 v12, vcc, s21, v12
	s_nop 1
	v_addc_co_u32_e32 v13, vcc, 0, v13, vcc
	global_load_dword v30, v[30:31], off nt
	s_nop 0
	global_load_dword v31, v[32:33], off nt
	s_nop 0
	global_load_dword v32, v[34:35], off nt
	global_load_dword v33, v[36:37], off nt
	s_nop 0
	global_load_dword v34, v[38:39], off nt
	global_load_dword v35, v[40:41], off nt
	global_load_dword v36, v[42:43], off nt
	s_nop 0
	global_load_dword v12, v[12:13], off nt
	s_waitcnt vmcnt(30)
	ds_write2_b32 v15, v11, v29 offset1:66
	s_waitcnt vmcnt(28)
	ds_write2_b32 v15, v46, v47 offset0:132 offset1:198
	s_waitcnt vmcnt(26)
	ds_write2_b32 v22, v48, v49 offset0:8 offset1:74
	s_waitcnt vmcnt(24)
; #define LAS __attribute__((address_space(3)))
; __device__ __forceinline__ unsigned pk2(float lo, float hi) { unsigned r; asm volatile("v_cvt_pk_bf16_f32 %0, %1, %2" : "=v"(r) : "v"(lo), "v"(hi)); return r; }
; __device__ __forceinline__ void p0_transpose_item(const float* W, int K, int N, bf16_t* WT, int mode, LAS float* scr, int item, int lane) {
;     ...
;     for (int i = 0; i < 32; ++i) scr[(2 * i + (lane >> 5)) * 33 + (lane & 31)] = v[i];
;     asm volatile("s_waitcnt lgkmcnt(0)" ::: "memory");
;     const int c = lane & 7;
; #pragma unroll
;     for (int j = 0; j < 4; ++j) { const int n = (lane >> 3) + 8 * j; const LAS float* s = scr + (8 * c) * 33 + n;
;         u32x4 o; o.x = pk2(s[0 * 33], s[1 * 33]); o.y = pk2(s[2 * 33], s[3 * 33]); o.z = pk2(s[4 * 33], s[5 * 33]); o.w = pk2(s[6 * 33], s[7 * 33]);
;         const int nn = n0 + n; const int drow = mode == 0 ? nn : ((nn >> 7) << 8) + (nn & 127) + (mode == 2 ? 128 : 0);
;         *(u32x4*)(WT + (size_t)drow * K + k0 + 8 * c) = o; }
	ds_write2_b32 v22, v50, v51 offset0:140 offset1:206
	s_waitcnt vmcnt(22)
	ds_write2_b32 v23, v52, v53 offset0:16 offset1:82
	s_waitcnt vmcnt(20)
	ds_write2_b32 v23, v54, v55 offset0:148 offset1:214
	s_waitcnt vmcnt(18)
	ds_write2_b32 v24, v56, v57 offset0:24 offset1:90
	s_waitcnt vmcnt(16)
	ds_write2_b32 v24, v58, v59 offset0:156 offset1:222
	s_waitcnt vmcnt(14)
	ds_write2_b32 v25, v60, v61 offset0:32 offset1:98
	s_waitcnt vmcnt(12)
	ds_write2_b32 v25, v62, v63 offset0:164 offset1:230
	s_waitcnt vmcnt(10)
	ds_write2_b32 v26, v64, v65 offset0:40 offset1:106
	s_waitcnt vmcnt(8)
	ds_write2_b32 v26, v66, v44 offset0:172 offset1:238
	s_waitcnt vmcnt(6)
	ds_write2_b32 v27, v30, v31 offset0:48 offset1:114
	s_waitcnt vmcnt(4)
	ds_write2_b32 v27, v32, v33 offset0:180 offset1:246
	s_waitcnt vmcnt(2)
	ds_write2_b32 v28, v34, v35 offset0:56 offset1:122
	s_waitcnt vmcnt(0)
	ds_write2_b32 v28, v36, v12 offset0:188 offset1:254
	s_waitcnt lgkmcnt(0)
	ds_read2_b32 v[12:13], v14 offset1:33
	v_lshl_add_u64 v[34:35], v[2:3], 0, s[6:7]
	s_and_b32 s6, s86, 0x60
	s_waitcnt lgkmcnt(0)
	v_cvt_pk_bf16_f32 v30, v12, v13
	ds_read2_b32 v[12:13], v14 offset0:66 offset1:99
	v_or_b32_e32 v11, s6, v17
	s_waitcnt lgkmcnt(0)
	v_cvt_pk_bf16_f32 v31, v12, v13
	ds_read2_b32 v[12:13], v14 offset0:132 offset1:165
	v_or_b32_e32 v11, s9, v11
	s_waitcnt lgkmcnt(0)
	v_cvt_pk_bf16_f32 v32, v12, v13
	ds_read2_b32 v[12:13], v14 offset0:198 offset1:231
	v_lshlrev_b32_e32 v36, 12, v11
	v_mov_b32_e32 v37, v1
	s_waitcnt lgkmcnt(0)
	v_cvt_pk_bf16_f32 v33, v12, v13
	ds_read2_b32 v[12:13], v14 offset0:8 offset1:41
	v_lshl_add_u64 v[36:37], v[34:35], 0, v[36:37]
	global_store_dwordx4 v[36:37], v[30:33], off nt
	v_or_b32_e32 v11, s6, v18
	v_or_b32_e32 v11, s9, v11
	s_waitcnt lgkmcnt(0)
	v_cvt_pk_bf16_f32 v30, v12, v13
	ds_read2_b32 v[12:13], v14 offset0:74 offset1:107
	s_waitcnt lgkmcnt(0)
	v_cvt_pk_bf16_f32 v31, v12, v13
	ds_read2_b32 v[12:13], v14 offset0:140 offset1:173
	s_waitcnt lgkmcnt(0)
	v_cvt_pk_bf16_f32 v32, v12, v13
	ds_read2_b32 v[12:13], v14 offset0:206 offset1:239
	v_lshlrev_b32_e32 v36, 12, v11
	v_mov_b32_e32 v37, v1
	s_waitcnt lgkmcnt(0)
	v_cvt_pk_bf16_f32 v33, v12, v13
	ds_read2_b32 v[12:13], v14 offset0:16 offset1:49
	v_lshl_add_u64 v[36:37], v[34:35], 0, v[36:37]
	global_store_dwordx4 v[36:37], v[30:33], off nt
	v_or_b32_e32 v11, s6, v19
	v_or_b32_e32 v11, s9, v11
	s_waitcnt lgkmcnt(0)
	v_cvt_pk_bf16_f32 v30, v12, v13
	ds_read2_b32 v[12:13], v14 offset0:82 offset1:115
	s_waitcnt lgkmcnt(0)
	v_cvt_pk_bf16_f32 v31, v12, v13
	ds_read2_b32 v[12:13], v14 offset0:148 offset1:181
	s_waitcnt lgkmcnt(0)
	v_cvt_pk_bf16_f32 v32, v12, v13
	ds_read2_b32 v[12:13], v14 offset0:214 offset1:247
	v_lshlrev_b32_e32 v36, 12, v11
	v_mov_b32_e32 v37, v1
	s_waitcnt lgkmcnt(0)
	v_cvt_pk_bf16_f32 v33, v12, v13
	ds_read2_b32 v[12:13], v14 offset0:24 offset1:57
	v_lshl_add_u64 v[36:37], v[34:35], 0, v[36:37]
	global_store_dwordx4 v[36:37], v[30:33], off nt
	v_or_b32_e32 v11, s6, v20
	v_or_b32_e32 v11, s9, v11
	s_waitcnt lgkmcnt(0)
	v_cvt_pk_bf16_f32 v30, v12, v13
	ds_read2_b32 v[12:13], v14 offset0:90 offset1:123
	s_waitcnt lgkmcnt(0)
	v_cvt_pk_bf16_f32 v31, v12, v13
	ds_read2_b32 v[12:13], v14 offset0:156 offset1:189
	s_waitcnt lgkmcnt(0)
	v_cvt_pk_bf16_f32 v32, v12, v13
	ds_read2_b32 v[12:13], v14 offset0:222 offset1:255
	s_waitcnt lgkmcnt(0)
	v_cvt_pk_bf16_f32 v33, v12, v13
	v_lshlrev_b32_e32 v12, 12, v11
	v_mov_b32_e32 v13, v1
	v_lshl_add_u64 v[12:13], v[34:35], 0, v[12:13]
	global_store_dwordx4 v[12:13], v[30:33], off nt
	s_waitcnt lgkmcnt(0)
	s_mov_b64 s[8:9], 0
.LBB0_146:
	s_andn2_b64 vcc, exec, s[8:9]
	s_cbranch_vccnz .LBB0_148
	s_load_dwordx2 s[8:9], s[4:5], 0x60
	s_add_i32 s6, s14, 0xffffd600
	s_lshr_b32 s6, s6, 5
	s_lshl_b64 s[86:87], s[6:7], 18
	v_mov_b32_e32 v13, v1
	s_waitcnt lgkmcnt(0)
; #define LAS __attribute__((address_space(3)))
; __device__ __forceinline__ unsigned pk2(float lo, float hi) { unsigned r; asm volatile("v_cvt_pk_bf16_f32 %0, %1, %2" : "=v"(r) : "v"(lo), "v"(hi)); return r; }
; __device__ __forceinline__ void p0_transpose_item(const float* W, int K, int N, bf16_t* WT, int mode, LAS float* scr, int item, int lane) {
;     ...
;     const float* wp = W + (size_t)(k0 + (lane >> 5)) * N + n0 + (lane & 31);
; #pragma unroll
;     for (int i = 0; i < 32; ++i) v[i] = __builtin_nontemporal_load(wp + (size_t)(2 * i) * N);
; #pragma unroll
;     for (int i = 0; i < 32; ++i) scr[(2 * i + (lane >> 5)) * 33 + (lane & 31)] = v[i];
;     asm volatile("s_waitcnt lgkmcnt(0)" ::: "memory");
;     const int c = lane & 7;
; #pragma unroll
;     for (int j = 0; j < 4; ++j) { const int n = (lane >> 3) + 8 * j; const LAS float* s = scr + (8 * c) * 33 + n;
;         u32x4 o; o.x = pk2(s[0 * 33], s[1 * 33]); o.y = pk2(s[2 * 33], s[3 * 33]); o.z = pk2(s[4 * 33], s[5 * 33]); o.w = pk2(s[6 * 33], s[7 * 33]);
;         const int nn = n0 + n; const int drow = mode == 0 ? nn : ((nn >> 7) << 8) + (nn & 127) + (mode == 2 ? 128 : 0);
;         *(u32x4*)(WT + (size_t)drow * K + k0 + 8 * c) = o; }
	s_add_u32 s88, s8, s86
	s_addc_u32 s89, s9, s87
	s_lshl_b64 s[86:87], s[6:7], 17
	s_add_u32 s9, s3, s86
	s_addc_u32 s86, s18, s87
	s_and_b32 s87, s12, 0xc0
	v_or_b32_e32 v11, s87, v16
	s_and_b32 s8, s11, 0xe0
	v_lshlrev_b32_e32 v12, 10, v11
	v_lshl_add_u64 v[12:13], s[88:89], 0, v[12:13]
	s_lshl_b32 s6, s8, 2
	v_lshl_add_u64 v[12:13], v[12:13], 0, s[6:7]
	v_lshl_add_u64 v[12:13], v[12:13], 0, v[0:1]
	v_add_co_u32_e32 v30, vcc, s22, v12
	s_lshl_b32 s6, s87, 1
	s_nop 0
	v_addc_co_u32_e32 v31, vcc, 0, v13, vcc
	v_add_co_u32_e32 v32, vcc, s23, v12
	s_add_u32 s88, s9, s6
	s_nop 0
	v_addc_co_u32_e32 v33, vcc, 0, v13, vcc
	v_add_co_u32_e32 v34, vcc, s25, v12
	s_addc_u32 s89, s86, 0
	s_nop 0
	v_addc_co_u32_e32 v35, vcc, 0, v13, vcc
	v_add_co_u32_e32 v36, vcc, s26, v12
	s_nop 1
	v_addc_co_u32_e32 v37, vcc, 0, v13, vcc
	global_load_dword v11, v[32:33], off offset:-4096 nt
	global_load_dword v29, v[32:33], off nt
	global_load_dword v48, v[32:33], off offset:2048 nt
	global_load_dword v49, v[36:37], off offset:-4096 nt
	global_load_dword v50, v[36:37], off nt
	v_add_co_u32_e32 v32, vcc, s27, v12
	s_nop 1
	v_addc_co_u32_e32 v33, vcc, 0, v13, vcc
	v_add_co_u32_e32 v38, vcc, s33, v12
	s_nop 1
	v_addc_co_u32_e32 v39, vcc, 0, v13, vcc
	v_add_co_u32_e32 v40, vcc, s34, v12
	s_nop 1
	v_addc_co_u32_e32 v41, vcc, 0, v13, vcc
	v_add_co_u32_e32 v42, vcc, s35, v12
	s_nop 1
	v_addc_co_u32_e32 v43, vcc, 0, v13, vcc
	v_add_co_u32_e32 v44, vcc, s36, v12
	s_nop 1
	v_addc_co_u32_e32 v45, vcc, 0, v13, vcc
	v_add_co_u32_e32 v46, vcc, s37, v12
	s_nop 1
	v_addc_co_u32_e32 v47, vcc, 0, v13, vcc
	global_load_dword v51, v[36:37], off offset:2048 nt
	global_load_dword v52, v[38:39], off offset:-4096 nt
	global_load_dword v53, v[38:39], off nt
	global_load_dword v54, v[38:39], off offset:2048 nt
	global_load_dword v55, v[42:43], off offset:-4096 nt
	global_load_dword v56, v[42:43], off nt
	s_nop 0
	global_load_dword v42, v[42:43], off offset:2048 nt
	s_nop 0
	global_load_dword v43, v[46:47], off offset:-4096 nt
	v_add_co_u32_e32 v36, vcc, s13, v12
	s_nop 1
	v_addc_co_u32_e32 v37, vcc, 0, v13, vcc
	v_add_co_u32_e32 v38, vcc, s38, v12
	global_load_dword v57, v[12:13], off nt
	global_load_dword v58, v[12:13], off offset:2048 nt
	global_load_dword v59, v[30:31], off offset:2048 nt
	s_nop 0
	global_load_dword v34, v[34:35], off offset:2048 nt
	s_nop 0
	global_load_dword v35, v[32:33], off offset:2048 nt
	s_nop 0
	global_load_dword v40, v[40:41], off offset:2048 nt
	s_nop 0
	global_load_dword v41, v[44:45], off offset:2048 nt
	s_nop 0
	global_load_dword v36, v[36:37], off offset:2048 nt
	v_addc_co_u32_e32 v39, vcc, 0, v13, vcc
	v_add_co_u32_e32 v30, vcc, s39, v12
	s_nop 1
	v_addc_co_u32_e32 v31, vcc, 0, v13, vcc
	v_add_co_u32_e32 v32, vcc, s40, v12
	s_nop 1
	v_addc_co_u32_e32 v33, vcc, 0, v13, vcc
	v_add_co_u32_e32 v12, vcc, s41, v12
	global_load_dword v37, v[46:47], off nt
	global_load_dword v44, v[46:47], off offset:2048 nt
	global_load_dword v45, v[38:39], off offset:-4096 nt
	s_nop 0
	global_load_dword v46, v[38:39], off nt
	s_nop 0
	global_load_dword v38, v[38:39], off offset:2048 nt
	s_nop 0
	global_load_dword v39, v[32:33], off offset:-4096 nt
	global_load_dword v47, v[32:33], off nt
	s_nop 0
	global_load_dword v32, v[32:33], off offset:2048 nt
	v_addc_co_u32_e32 v13, vcc, 0, v13, vcc
	global_load_dword v30, v[30:31], off offset:2048 nt
	s_nop 0
	global_load_dword v31, v[12:13], off nt
	s_nop 0
	global_load_dword v12, v[12:13], off offset:2048 nt
	s_waitcnt vmcnt(17)
	ds_write2_b32 v15, v57, v58 offset1:66
	s_waitcnt vmcnt(16)
	ds_write2_b32 v15, v11, v59 offset0:132 offset1:198
	ds_write2_b32 v22, v29, v48 offset0:8 offset1:74
	s_waitcnt vmcnt(15)
	ds_write2_b32 v22, v49, v34 offset0:140 offset1:206
	ds_write2_b32 v23, v50, v51 offset0:16 offset1:82
	s_waitcnt vmcnt(14)
	ds_write2_b32 v23, v52, v35 offset0:148 offset1:214
	ds_write2_b32 v24, v53, v54 offset0:24 offset1:90
	s_waitcnt vmcnt(13)
	ds_write2_b32 v24, v55, v40 offset0:156 offset1:222
	ds_write2_b32 v25, v56, v42 offset0:32 offset1:98
	s_waitcnt vmcnt(12)
	ds_write2_b32 v25, v43, v41 offset0:164 offset1:230
	s_waitcnt vmcnt(9)
	ds_write2_b32 v26, v37, v44 offset0:40 offset1:106
	s_waitcnt vmcnt(8)
	ds_write2_b32 v26, v45, v36 offset0:172 offset1:238
	s_waitcnt vmcnt(6)
	ds_write2_b32 v27, v46, v38 offset0:48 offset1:114
	s_waitcnt vmcnt(2)
	ds_write2_b32 v27, v39, v30 offset0:180 offset1:246
	ds_write2_b32 v28, v47, v32 offset0:56 offset1:122
	s_waitcnt vmcnt(0)
	ds_write2_b32 v28, v31, v12 offset0:188 offset1:254
	s_waitcnt lgkmcnt(0)
	ds_read2_b32 v[12:13], v14 offset1:33
	s_waitcnt lgkmcnt(0)
	v_cvt_pk_bf16_f32 v30, v12, v13
	ds_read2_b32 v[12:13], v14 offset0:66 offset1:99
	v_mov_b32_e32 v11, v1
	s_waitcnt lgkmcnt(0)
	v_cvt_pk_bf16_f32 v31, v12, v13
	ds_read2_b32 v[12:13], v14 offset0:132 offset1:165
	v_lshl_add_u64 v[34:35], s[88:89], 0, v[10:11]
	v_or_b32_e32 v11, s8, v17
	s_waitcnt lgkmcnt(0)
	v_cvt_pk_bf16_f32 v32, v12, v13
	ds_read2_b32 v[12:13], v14 offset0:198 offset1:231
	v_lshlrev_b32_e32 v36, 9, v11
	v_mov_b32_e32 v37, v1
	s_waitcnt lgkmcnt(0)
	v_cvt_pk_bf16_f32 v33, v12, v13
	ds_read2_b32 v[12:13], v14 offset0:8 offset1:41
	v_lshl_add_u64 v[36:37], v[34:35], 0, v[36:37]
	global_store_dwordx4 v[36:37], v[30:33], off nt
	v_or_b32_e32 v11, s8, v18
	v_lshlrev_b32_e32 v36, 9, v11
	s_waitcnt lgkmcnt(0)
	v_cvt_pk_bf16_f32 v30, v12, v13
	ds_read2_b32 v[12:13], v14 offset0:74 offset1:107
	s_waitcnt lgkmcnt(0)
	v_cvt_pk_bf16_f32 v31, v12, v13
	ds_read2_b32 v[12:13], v14 offset0:140 offset1:173
	s_waitcnt lgkmcnt(0)
	v_cvt_pk_bf16_f32 v32, v12, v13
	ds_read2_b32 v[12:13], v14 offset0:206 offset1:239
	v_mov_b32_e32 v37, v1
	s_waitcnt lgkmcnt(0)
	v_cvt_pk_bf16_f32 v33, v12, v13
	ds_read2_b32 v[12:13], v14 offset0:16 offset1:49
	v_lshl_add_u64 v[36:37], v[34:35], 0, v[36:37]
	global_store_dwordx4 v[36:37], v[30:33], off nt
	v_or_b32_e32 v11, s8, v19
	v_lshlrev_b32_e32 v36, 9, v11
	s_waitcnt lgkmcnt(0)
	v_cvt_pk_bf16_f32 v30, v12, v13
	ds_read2_b32 v[12:13], v14 offset0:82 offset1:115
	s_waitcnt lgkmcnt(0)
	v_cvt_pk_bf16_f32 v31, v12, v13
	ds_read2_b32 v[12:13], v14 offset0:148 offset1:181
	s_waitcnt lgkmcnt(0)
	v_cvt_pk_bf16_f32 v32, v12, v13
	ds_read2_b32 v[12:13], v14 offset0:214 offset1:247
	v_mov_b32_e32 v37, v1
	s_waitcnt lgkmcnt(0)
	v_cvt_pk_bf16_f32 v33, v12, v13
	ds_read2_b32 v[12:13], v14 offset0:24 offset1:57
	v_lshl_add_u64 v[36:37], v[34:35], 0, v[36:37]
	global_store_dwordx4 v[36:37], v[30:33], off nt
	v_or_b32_e32 v11, s8, v20
	s_waitcnt lgkmcnt(0)
	v_cvt_pk_bf16_f32 v30, v12, v13
	ds_read2_b32 v[12:13], v14 offset0:90 offset1:123
	s_waitcnt lgkmcnt(0)
	v_cvt_pk_bf16_f32 v31, v12, v13
	ds_read2_b32 v[12:13], v14 offset0:156 offset1:189
	s_waitcnt lgkmcnt(0)
	v_cvt_pk_bf16_f32 v32, v12, v13
	ds_read2_b32 v[12:13], v14 offset0:222 offset1:255
	s_waitcnt lgkmcnt(0)
	v_cvt_pk_bf16_f32 v33, v12, v13
	v_lshlrev_b32_e32 v12, 9, v11
	v_mov_b32_e32 v13, v1
	v_lshl_add_u64 v[12:13], v[34:35], 0, v[12:13]
	global_store_dwordx4 v[12:13], v[30:33], off nt
	s_waitcnt lgkmcnt(0)

; #define LAS __attribute__((address_space(3)))
; __device__ __forceinline__ void p0_transpose_item(const float* W, int K, int N, bf16_t* WT, int mode, LAS float* scr, int item, int lane) {
;     const int nblk = N / 32, kb = item / nblk, nb = item % nblk, k0 = 64 * kb, n0 = 32 * nb;
;     float v[32];
;     const float* wp = W + (size_t)(k0 + (lane >> 5)) * N + n0 + (lane & 31);
; #pragma unroll
;     for (int i = 0; i < 32; ++i) v[i] = __builtin_nontemporal_load(wp + (size_t)(2 * i) * N);
.LBB0_149:
	s_andn2_b64 vcc, exec, s[8:9]
	s_cbranch_vccnz .LBB0_151
	s_load_dwordx2 s[86:87], s[4:5], 0x70
	s_add_i32 s6, s14, 0xde00
	s_and_b32 s9, s6, 0xffc0
	v_or_b32_e32 v11, s9, v16
	s_and_b32 s8, s11, 0x7e0
	v_lshlrev_b32_e32 v12, 13, v11
	v_mov_b32_e32 v13, v1
	s_waitcnt lgkmcnt(0)
	v_lshl_add_u64 v[12:13], s[86:87], 0, v[12:13]
	s_lshl_b32 s6, s8, 2
	v_lshl_add_u64 v[12:13], v[12:13], 0, s[6:7]
	v_lshl_add_u64 v[12:13], v[12:13], 0, v[0:1]
	v_add_co_u32_e32 v30, vcc, s26, v12
	s_lshl_b32 s6, s9, 1
	s_nop 0
	v_addc_co_u32_e32 v31, vcc, 0, v13, vcc
	v_add_co_u32_e32 v32, vcc, s35, v12
	s_nop 1
	v_addc_co_u32_e32 v33, vcc, 0, v13, vcc
	v_add_co_u32_e32 v34, vcc, s38, v12
	s_nop 1
	v_addc_co_u32_e32 v35, vcc, 0, v13, vcc
	v_add_co_u32_e32 v36, vcc, s42, v12
	s_nop 1
	v_addc_co_u32_e32 v37, vcc, 0, v13, vcc
	v_add_co_u32_e32 v38, vcc, s43, v12
	s_nop 1
	v_addc_co_u32_e32 v39, vcc, 0, v13, vcc
	v_add_co_u32_e32 v40, vcc, s44, v12
	s_nop 1
	v_addc_co_u32_e32 v41, vcc, 0, v13, vcc
	v_add_co_u32_e32 v42, vcc, s45, v12
	s_nop 1
	v_addc_co_u32_e32 v43, vcc, 0, v13, vcc
	global_load_dword v11, v[12:13], off nt
	global_load_dword v29, v[30:31], off nt
	global_load_dword v46, v[32:33], off nt
	global_load_dword v47, v[34:35], off nt
	global_load_dword v48, v[36:37], off nt
	global_load_dword v49, v[38:39], off nt
	global_load_dword v50, v[40:41], off nt
	global_load_dword v51, v[42:43], off nt
	v_add_co_u32_e32 v30, vcc, s46, v12
	s_nop 1
	v_addc_co_u32_e32 v31, vcc, 0, v13, vcc
	v_add_co_u32_e32 v32, vcc, s47, v12
	s_nop 1
	v_addc_co_u32_e32 v33, vcc, 0, v13, vcc
	v_add_co_u32_e32 v34, vcc, s48, v12
	s_nop 1
	v_addc_co_u32_e32 v35, vcc, 0, v13, vcc
	v_add_co_u32_e32 v36, vcc, s10, v12
	s_nop 1
	v_addc_co_u32_e32 v37, vcc, 0, v13, vcc
	v_add_co_u32_e32 v38, vcc, s49, v12
	s_nop 1
	v_addc_co_u32_e32 v39, vcc, 0, v13, vcc
	v_add_co_u32_e32 v40, vcc, s50, v12
	s_nop 1
	v_addc_co_u32_e32 v41, vcc, 0, v13, vcc
	v_add_co_u32_e32 v42, vcc, s51, v12
	s_nop 1
	v_addc_co_u32_e32 v43, vcc, 0, v13, vcc
	v_add_co_u32_e32 v44, vcc, s52, v12
	s_nop 1
	v_addc_co_u32_e32 v45, vcc, 0, v13, vcc
	global_load_dword v52, v[30:31], off nt
	global_load_dword v53, v[32:33], off nt
	global_load_dword v54, v[34:35], off nt
	global_load_dword v55, v[36:37], off nt
	global_load_dword v56, v[38:39], off nt
	global_load_dword v57, v[40:41], off nt
	global_load_dword v58, v[42:43], off nt
	global_load_dword v59, v[44:45], off nt
	v_add_co_u32_e32 v30, vcc, s53, v12
	s_nop 1
	v_addc_co_u32_e32 v31, vcc, 0, v13, vcc
	v_add_co_u32_e32 v32, vcc, s54, v12
	s_nop 1
	v_addc_co_u32_e32 v33, vcc, 0, v13, vcc
	v_add_co_u32_e32 v34, vcc, s55, v12
	s_nop 1
	v_addc_co_u32_e32 v35, vcc, 0, v13, vcc
	v_add_co_u32_e32 v36, vcc, s56, v12
	s_nop 1
	v_addc_co_u32_e32 v37, vcc, 0, v13, vcc
	v_add_co_u32_e32 v38, vcc, s57, v12
	s_nop 1
	v_addc_co_u32_e32 v39, vcc, 0, v13, vcc
	v_add_co_u32_e32 v40, vcc, s58, v12
	s_nop 1
	v_addc_co_u32_e32 v41, vcc, 0, v13, vcc
	v_add_co_u32_e32 v42, vcc, s16, v12
	s_nop 1
	v_addc_co_u32_e32 v43, vcc, 0, v13, vcc
	v_add_co_u32_e32 v44, vcc, s59, v12
	s_nop 1
	v_addc_co_u32_e32 v45, vcc, 0, v13, vcc
	global_load_dword v60, v[30:31], off nt
	global_load_dword v61, v[32:33], off nt
	global_load_dword v62, v[34:35], off nt
	global_load_dword v63, v[36:37], off nt
	global_load_dword v64, v[38:39], off nt
	global_load_dword v65, v[40:41], off nt
	global_load_dword v66, v[42:43], off nt
	s_nop 0
	global_load_dword v44, v[44:45], off nt
	v_add_co_u32_e32 v30, vcc, s60, v12
	s_nop 1
	v_addc_co_u32_e32 v31, vcc, 0, v13, vcc
	v_add_co_u32_e32 v32, vcc, s61, v12
	s_nop 1
	v_addc_co_u32_e32 v33, vcc, 0, v13, vcc
	v_add_co_u32_e32 v34, vcc, s62, v12
	s_nop 1
	v_addc_co_u32_e32 v35, vcc, 0, v13, vcc
	v_add_co_u32_e32 v36, vcc, s63, v12
	s_nop 1
	v_addc_co_u32_e32 v37, vcc, 0, v13, vcc
	v_add_co_u32_e32 v38, vcc, s64, v12
	s_nop 1
	v_addc_co_u32_e32 v39, vcc, 0, v13, vcc
	v_add_co_u32_e32 v40, vcc, s65, v12
	s_nop 1
	v_addc_co_u32_e32 v41, vcc, 0, v13, vcc
	v_add_co_u32_e32 v42, vcc, s66, v12
	s_nop 1
	v_addc_co_u32_e32 v43, vcc, 0, v13, vcc
	v_add_co_u32_e32 v12, vcc, s67, v12
	s_nop 1
	v_addc_co_u32_e32 v13, vcc, 0, v13, vcc
	global_load_dword v30, v[30:31], off nt
	s_nop 0
	global_load_dword v31, v[32:33], off nt
	s_nop 0
	global_load_dword v32, v[34:35], off nt
	global_load_dword v33, v[36:37], off nt
	s_nop 0
	global_load_dword v34, v[38:39], off nt
	global_load_dword v35, v[40:41], off nt
	global_load_dword v36, v[42:43], off nt
	s_nop 0
	global_load_dword v12, v[12:13], off nt
	s_waitcnt vmcnt(30)
; #define LAS __attribute__((address_space(3)))
; __device__ __forceinline__ unsigned pk2(float lo, float hi) { unsigned r; asm volatile("v_cvt_pk_bf16_f32 %0, %1, %2" : "=v"(r) : "v"(lo), "v"(hi)); return r; }
; __device__ __forceinline__ void p0_transpose_item(const float* W, int K, int N, bf16_t* WT, int mode, LAS float* scr, int item, int lane) {
;     ...
;     for (int i = 0; i < 32; ++i) scr[(2 * i + (lane >> 5)) * 33 + (lane & 31)] = v[i];
;     asm volatile("s_waitcnt lgkmcnt(0)" ::: "memory");
;     const int c = lane & 7;
; #pragma unroll
;     for (int j = 0; j < 4; ++j) { const int n = (lane >> 3) + 8 * j; const LAS float* s = scr + (8 * c) * 33 + n;
;         u32x4 o; o.x = pk2(s[0 * 33], s[1 * 33]); o.y = pk2(s[2 * 33], s[3 * 33]); o.z = pk2(s[4 * 33], s[5 * 33]); o.w = pk2(s[6 * 33], s[7 * 33]);
;         const int nn = n0 + n; const int drow = mode == 0 ? nn : ((nn >> 7) << 8) + (nn & 127) + (mode == 2 ? 128 : 0);
;         *(u32x4*)(WT + (size_t)drow * K + k0 + 8 * c) = o; }
	ds_write2_b32 v15, v11, v29 offset1:66
	s_waitcnt vmcnt(28)
	ds_write2_b32 v15, v46, v47 offset0:132 offset1:198
	s_waitcnt vmcnt(26)
	ds_write2_b32 v22, v48, v49 offset0:8 offset1:74
	s_waitcnt vmcnt(24)
	ds_write2_b32 v22, v50, v51 offset0:140 offset1:206
	s_waitcnt vmcnt(22)
	ds_write2_b32 v23, v52, v53 offset0:16 offset1:82
	s_waitcnt vmcnt(20)
	ds_write2_b32 v23, v54, v55 offset0:148 offset1:214
	s_waitcnt vmcnt(18)
	ds_write2_b32 v24, v56, v57 offset0:24 offset1:90
	s_waitcnt vmcnt(16)
	ds_write2_b32 v24, v58, v59 offset0:156 offset1:222
	s_waitcnt vmcnt(14)
	ds_write2_b32 v25, v60, v61 offset0:32 offset1:98
	s_waitcnt vmcnt(12)
	ds_write2_b32 v25, v62, v63 offset0:164 offset1:230
	s_waitcnt vmcnt(10)
	ds_write2_b32 v26, v64, v65 offset0:40 offset1:106
	s_waitcnt vmcnt(8)
	ds_write2_b32 v26, v66, v44 offset0:172 offset1:238
	s_waitcnt vmcnt(6)
	ds_write2_b32 v27, v30, v31 offset0:48 offset1:114
	s_waitcnt vmcnt(4)
	ds_write2_b32 v27, v32, v33 offset0:180 offset1:246
	s_waitcnt vmcnt(2)
	ds_write2_b32 v28, v34, v35 offset0:56 offset1:122
	s_waitcnt vmcnt(0)
	ds_write2_b32 v28, v36, v12 offset0:188 offset1:254
	s_waitcnt lgkmcnt(0)
	ds_read2_b32 v[12:13], v14 offset1:33
	s_waitcnt lgkmcnt(0)
	v_cvt_pk_bf16_f32 v30, v12, v13
	ds_read2_b32 v[12:13], v14 offset0:66 offset1:99
	s_waitcnt lgkmcnt(0)
	v_cvt_pk_bf16_f32 v31, v12, v13
	ds_read2_b32 v[12:13], v14 offset0:132 offset1:165
	v_or_b32_e32 v11, s8, v17
	s_waitcnt lgkmcnt(0)
	v_cvt_pk_bf16_f32 v32, v12, v13
	ds_read2_b32 v[12:13], v14 offset0:198 offset1:231
	v_lshl_add_u64 v[34:35], v[4:5], 0, s[6:7]
	v_lshlrev_b32_e32 v36, 12, v11
	v_mov_b32_e32 v37, v1
	s_waitcnt lgkmcnt(0)
	v_cvt_pk_bf16_f32 v33, v12, v13
	ds_read2_b32 v[12:13], v14 offset0:8 offset1:41
	v_lshl_add_u64 v[36:37], v[34:35], 0, v[36:37]
	global_store_dwordx4 v[36:37], v[30:33], off nt
	v_or_b32_e32 v11, s8, v18
	v_lshlrev_b32_e32 v36, 12, v11
	s_waitcnt lgkmcnt(0)
	v_cvt_pk_bf16_f32 v30, v12, v13
	ds_read2_b32 v[12:13], v14 offset0:74 offset1:107
	s_waitcnt lgkmcnt(0)
	v_cvt_pk_bf16_f32 v31, v12, v13
	ds_read2_b32 v[12:13], v14 offset0:140 offset1:173
	s_waitcnt lgkmcnt(0)
	v_cvt_pk_bf16_f32 v32, v12, v13
	ds_read2_b32 v[12:13], v14 offset0:206 offset1:239
	v_mov_b32_e32 v37, v1
	s_waitcnt lgkmcnt(0)
	v_cvt_pk_bf16_f32 v33, v12, v13
	ds_read2_b32 v[12:13], v14 offset0:16 offset1:49
	v_lshl_add_u64 v[36:37], v[34:35], 0, v[36:37]
	global_store_dwordx4 v[36:37], v[30:33], off nt
	v_or_b32_e32 v11, s8, v19
	v_lshlrev_b32_e32 v36, 12, v11
	s_waitcnt lgkmcnt(0)
	v_cvt_pk_bf16_f32 v30, v12, v13
	ds_read2_b32 v[12:13], v14 offset0:82 offset1:115
	s_waitcnt lgkmcnt(0)
	v_cvt_pk_bf16_f32 v31, v12, v13
	ds_read2_b32 v[12:13], v14 offset0:148 offset1:181
	s_waitcnt lgkmcnt(0)
	v_cvt_pk_bf16_f32 v32, v12, v13
	ds_read2_b32 v[12:13], v14 offset0:214 offset1:247
	v_mov_b32_e32 v37, v1
	s_waitcnt lgkmcnt(0)
	v_cvt_pk_bf16_f32 v33, v12, v13
	ds_read2_b32 v[12:13], v14 offset0:24 offset1:57
	v_lshl_add_u64 v[36:37], v[34:35], 0, v[36:37]
	global_store_dwordx4 v[36:37], v[30:33], off nt
	v_or_b32_e32 v11, s8, v20
	s_waitcnt lgkmcnt(0)
	v_cvt_pk_bf16_f32 v30, v12, v13
	ds_read2_b32 v[12:13], v14 offset0:90 offset1:123
	s_waitcnt lgkmcnt(0)
	v_cvt_pk_bf16_f32 v31, v12, v13
	ds_read2_b32 v[12:13], v14 offset0:156 offset1:189
	s_waitcnt lgkmcnt(0)
	v_cvt_pk_bf16_f32 v32, v12, v13
	ds_read2_b32 v[12:13], v14 offset0:222 offset1:255
	s_waitcnt lgkmcnt(0)
	v_cvt_pk_bf16_f32 v33, v12, v13
	v_lshlrev_b32_e32 v12, 12, v11
	v_mov_b32_e32 v13, v1
	v_lshl_add_u64 v[12:13], v[34:35], 0, v[12:13]
	global_store_dwordx4 v[12:13], v[30:33], off nt
	s_waitcnt lgkmcnt(0)

; #define LAS __attribute__((address_space(3)))
; __device__ __forceinline__ void p0_transpose_item(const float* W, int K, int N, bf16_t* WT, int mode, LAS float* scr, int item, int lane) {
;     const int nblk = N / 32, kb = item / nblk, nb = item % nblk, k0 = 64 * kb, n0 = 32 * nb;
;     float v[32];
;     const float* wp = W + (size_t)(k0 + (lane >> 5)) * N + n0 + (lane & 31);
; #pragma unroll
;     for (int i = 0; i < 32; ++i) v[i] = __builtin_nontemporal_load(wp + (size_t)(2 * i) * N);
; #pragma unroll
;     for (int i = 0; i < 32; ++i) scr[(2 * i + (lane >> 5)) * 33 + (lane & 31)] = v[i];
.LBB0_605:
	s_cmpk_gt_i32 s86, 0x15ff
	s_mov_b64 s[16:17], -1
	s_cbranch_scc0 .LBB0_607
	s_load_dwordx2 s[88:89], s[8:9], 0x90
	s_and_b32 s14, s86, 0x7fffffc0
	s_add_i32 s16, s14, 0xffffea00
	v_or_b32_e32 v6, s16, v10
	v_mov_b32_e32 v7, v1
	s_and_b32 s20, s5, 0x7e0
	v_lshlrev_b64 v[6:7], 13, v[6:7]
	s_waitcnt lgkmcnt(0)
	v_lshl_add_u64 v[6:7], s[88:89], 0, v[6:7]
	s_lshl_b32 s14, s20, 2
	v_lshl_add_u64 v[6:7], v[6:7], 0, s[14:15]
	v_lshl_add_u64 v[6:7], v[6:7], 0, v[0:1]
	s_movk_i32 s14, 0x4000
	v_add_co_u32_e32 v24, vcc, s14, v6
	s_mov_b32 s14, 0x8000
	s_nop 0
	v_addc_co_u32_e32 v25, vcc, 0, v7, vcc
	global_load_dword v26, v[6:7], off nt
	global_load_dword v27, v[24:25], off nt
	v_add_co_u32_e32 v24, vcc, s14, v6
	s_mov_b32 s17, s15
	s_nop 0
	v_addc_co_u32_e32 v25, vcc, 0, v7, vcc
	global_load_dword v28, v[24:25], off nt
	v_add_co_u32_e32 v24, vcc, s19, v6
	s_nop 1
	v_addc_co_u32_e32 v25, vcc, 0, v7, vcc
	global_load_dword v29, v[24:25], off nt
	v_add_co_u32_e32 v24, vcc, s22, v6
	s_nop 1
	v_addc_co_u32_e32 v25, vcc, 0, v7, vcc
	global_load_dword v30, v[24:25], off nt
	v_add_co_u32_e32 v24, vcc, s23, v6
	s_nop 1
	v_addc_co_u32_e32 v25, vcc, 0, v7, vcc
	global_load_dword v31, v[24:25], off nt
	v_add_co_u32_e32 v24, vcc, s25, v6
	s_nop 1
	v_addc_co_u32_e32 v25, vcc, 0, v7, vcc
	global_load_dword v32, v[24:25], off nt
	v_add_co_u32_e32 v24, vcc, s26, v6
	s_nop 1
	v_addc_co_u32_e32 v25, vcc, 0, v7, vcc
	global_load_dword v33, v[24:25], off nt
	v_add_co_u32_e32 v24, vcc, s27, v6
	s_nop 1
	v_addc_co_u32_e32 v25, vcc, 0, v7, vcc
	global_load_dword v34, v[24:25], off nt
	v_add_co_u32_e32 v24, vcc, s33, v6
	s_nop 1
	v_addc_co_u32_e32 v25, vcc, 0, v7, vcc
	global_load_dword v35, v[24:25], off nt
	v_add_co_u32_e32 v24, vcc, s34, v6
	s_nop 1
	v_addc_co_u32_e32 v25, vcc, 0, v7, vcc
	global_load_dword v36, v[24:25], off nt
	v_add_co_u32_e32 v24, vcc, s35, v6
	s_nop 1
	v_addc_co_u32_e32 v25, vcc, 0, v7, vcc
	global_load_dword v37, v[24:25], off nt
	v_add_co_u32_e32 v24, vcc, s36, v6
	s_nop 1
	v_addc_co_u32_e32 v25, vcc, 0, v7, vcc
	global_load_dword v38, v[24:25], off nt
	v_add_co_u32_e32 v24, vcc, s37, v6
	s_nop 1
	v_addc_co_u32_e32 v25, vcc, 0, v7, vcc
	global_load_dword v39, v[24:25], off nt
	v_add_co_u32_e32 v24, vcc, s38, v6
	s_nop 1
	v_addc_co_u32_e32 v25, vcc, 0, v7, vcc
	global_load_dword v40, v[24:25], off nt
	v_add_co_u32_e32 v24, vcc, s39, v6
	s_nop 1
	v_addc_co_u32_e32 v25, vcc, 0, v7, vcc
	global_load_dword v41, v[24:25], off nt
	v_add_co_u32_e32 v24, vcc, s40, v6
	s_nop 1
	v_addc_co_u32_e32 v25, vcc, 0, v7, vcc
	global_load_dword v42, v[24:25], off nt
	v_add_co_u32_e32 v24, vcc, s41, v6
	s_nop 1
	v_addc_co_u32_e32 v25, vcc, 0, v7, vcc
	global_load_dword v43, v[24:25], off nt
	v_add_co_u32_e32 v24, vcc, s42, v6
	s_nop 1
	v_addc_co_u32_e32 v25, vcc, 0, v7, vcc
	global_load_dword v44, v[24:25], off nt
	v_add_co_u32_e32 v24, vcc, s43, v6
	s_nop 1
	v_addc_co_u32_e32 v25, vcc, 0, v7, vcc
	global_load_dword v45, v[24:25], off nt
	v_add_co_u32_e32 v24, vcc, s44, v6
	s_nop 1
	v_addc_co_u32_e32 v25, vcc, 0, v7, vcc
	global_load_dword v46, v[24:25], off nt
	v_add_co_u32_e32 v24, vcc, s45, v6
	s_nop 1
	v_addc_co_u32_e32 v25, vcc, 0, v7, vcc
	global_load_dword v47, v[24:25], off nt
	v_add_co_u32_e32 v24, vcc, s46, v6
	s_nop 1
	v_addc_co_u32_e32 v25, vcc, 0, v7, vcc
	global_load_dword v48, v[24:25], off nt
	v_add_co_u32_e32 v24, vcc, s47, v6
	s_nop 1
	v_addc_co_u32_e32 v25, vcc, 0, v7, vcc
	global_load_dword v49, v[24:25], off nt
	v_add_co_u32_e32 v24, vcc, s48, v6
	s_nop 1
	v_addc_co_u32_e32 v25, vcc, 0, v7, vcc
	global_load_dword v50, v[24:25], off nt
	v_add_co_u32_e32 v24, vcc, s49, v6
	s_nop 1
	v_addc_co_u32_e32 v25, vcc, 0, v7, vcc
	global_load_dword v51, v[24:25], off nt
	v_add_co_u32_e32 v24, vcc, s50, v6
	s_nop 1
	v_addc_co_u32_e32 v25, vcc, 0, v7, vcc
	global_load_dword v52, v[24:25], off nt
	v_add_co_u32_e32 v24, vcc, s51, v6
	s_nop 1
	v_addc_co_u32_e32 v25, vcc, 0, v7, vcc
	global_load_dword v53, v[24:25], off nt
	v_add_co_u32_e32 v24, vcc, s52, v6
	s_nop 1
	v_addc_co_u32_e32 v25, vcc, 0, v7, vcc
	global_load_dword v54, v[24:25], off nt
	v_add_co_u32_e32 v24, vcc, s53, v6
	s_nop 1
	v_addc_co_u32_e32 v25, vcc, 0, v7, vcc
	global_load_dword v55, v[24:25], off nt
	v_add_co_u32_e32 v24, vcc, s54, v6
	s_nop 1
	v_addc_co_u32_e32 v25, vcc, 0, v7, vcc
	v_add_co_u32_e32 v6, vcc, s55, v6
	global_load_dword v24, v[24:25], off nt
	s_nop 0
	v_addc_co_u32_e32 v7, vcc, 0, v7, vcc
	global_load_dword v6, v[6:7], off nt
	s_waitcnt vmcnt(30)
	ds_write2_b32 v16, v26, v27 offset1:66
	s_waitcnt vmcnt(28)
	ds_write2_b32 v16, v28, v29 offset0:132 offset1:198
	s_waitcnt vmcnt(26)
	ds_write2_b32 v17, v30, v31 offset0:8 offset1:74
	s_waitcnt vmcnt(24)
	ds_write2_b32 v17, v32, v33 offset0:140 offset1:206
	s_waitcnt vmcnt(22)
	ds_write2_b32 v18, v34, v35 offset0:16 offset1:82
	s_waitcnt vmcnt(20)
	ds_write2_b32 v18, v36, v37 offset0:148 offset1:214
	s_waitcnt vmcnt(18)
	ds_write2_b32 v19, v38, v39 offset0:24 offset1:90
	s_waitcnt vmcnt(16)
	ds_write2_b32 v19, v40, v41 offset0:156 offset1:222
	s_waitcnt vmcnt(14)
	ds_write2_b32 v20, v42, v43 offset0:32 offset1:98
	s_waitcnt vmcnt(12)
	ds_write2_b32 v20, v44, v45 offset0:164 offset1:230
	s_waitcnt vmcnt(10)
	ds_write2_b32 v21, v46, v47 offset0:40 offset1:106
	s_waitcnt vmcnt(8)
	ds_write2_b32 v21, v48, v49 offset0:172 offset1:238
	s_waitcnt vmcnt(6)
	ds_write2_b32 v22, v50, v51 offset0:48 offset1:114
	s_waitcnt vmcnt(4)
	ds_write2_b32 v22, v52, v53 offset0:180 offset1:246
	s_waitcnt vmcnt(2)
	ds_write2_b32 v23, v54, v55 offset0:56 offset1:122
	s_waitcnt vmcnt(0)
	ds_write2_b32 v23, v24, v6 offset0:188 offset1:254
	s_waitcnt lgkmcnt(0)
; #define LAS __attribute__((address_space(3)))
; __device__ __forceinline__ unsigned pk2(float lo, float hi) { unsigned r; asm volatile("v_cvt_pk_bf16_f32 %0, %1, %2" : "=v"(r) : "v"(lo), "v"(hi)); return r; }
; __device__ __forceinline__ void p0_transpose_item(const float* W, int K, int N, bf16_t* WT, int mode, LAS float* scr, int item, int lane) {
;     ...
;     const int c = lane & 7;
; #pragma unroll
;     for (int j = 0; j < 4; ++j) { const int n = (lane >> 3) + 8 * j; const LAS float* s = scr + (8 * c) * 33 + n;
;         u32x4 o; o.x = pk2(s[0 * 33], s[1 * 33]); o.y = pk2(s[2 * 33], s[3 * 33]); o.z = pk2(s[4 * 33], s[5 * 33]); o.w = pk2(s[6 * 33], s[7 * 33]);
;         const int nn = n0 + n; const int drow = mode == 0 ? nn : ((nn >> 7) << 8) + (nn & 127) + (mode == 2 ? 128 : 0);
;         *(u32x4*)(WT + (size_t)drow * K + k0 + 8 * c) = o; }
	ds_read2_b32 v[24:25], v12 offset1:33
	s_waitcnt lgkmcnt(0)
	v_cvt_pk_bf16_f32 v24, v24, v25
	ds_read2_b32 v[26:27], v12 offset0:66 offset1:99
	s_waitcnt lgkmcnt(0)
	v_cvt_pk_bf16_f32 v25, v26, v27
	ds_read2_b32 v[26:27], v12 offset0:132 offset1:165
	s_waitcnt lgkmcnt(0)
	v_cvt_pk_bf16_f32 v26, v26, v27
	ds_read2_b32 v[28:29], v12 offset0:198 offset1:231
	s_waitcnt lgkmcnt(0)
	v_cvt_pk_bf16_f32 v27, v28, v29
	v_or_b32_e32 v28, s20, v11
	v_mul_u32_u24_e32 v28, 0x1600, v28
	v_lshl_add_u64 v[6:7], s[16:17], 1, v[2:3]
	v_lshlrev_b32_e32 v28, 1, v28
	v_mov_b32_e32 v29, v1
	v_lshl_add_u64 v[28:29], v[6:7], 0, v[28:29]
	global_store_dwordx4 v[28:29], v[24:27], off nt
	ds_read2_b32 v[24:25], v12 offset0:8 offset1:41
	s_mov_b64 s[16:17], 0
	s_waitcnt lgkmcnt(0)
	v_cvt_pk_bf16_f32 v24, v24, v25
	ds_read2_b32 v[26:27], v12 offset0:74 offset1:107
	s_waitcnt lgkmcnt(0)
	v_cvt_pk_bf16_f32 v25, v26, v27
	ds_read2_b32 v[26:27], v12 offset0:140 offset1:173
	s_waitcnt lgkmcnt(0)
	v_cvt_pk_bf16_f32 v26, v26, v27
	ds_read2_b32 v[28:29], v12 offset0:206 offset1:239
	s_waitcnt lgkmcnt(0)
	v_cvt_pk_bf16_f32 v27, v28, v29
	v_or_b32_e32 v28, s20, v13
	v_mul_u32_u24_e32 v28, 0x1600, v28
	v_lshlrev_b32_e32 v28, 1, v28
	v_mov_b32_e32 v29, v1
	v_lshl_add_u64 v[28:29], v[6:7], 0, v[28:29]
	global_store_dwordx4 v[28:29], v[24:27], off nt
	ds_read2_b32 v[24:25], v12 offset0:16 offset1:49
	s_waitcnt lgkmcnt(0)
	v_cvt_pk_bf16_f32 v24, v24, v25
	ds_read2_b32 v[26:27], v12 offset0:82 offset1:115
	s_waitcnt lgkmcnt(0)
	v_cvt_pk_bf16_f32 v25, v26, v27
	ds_read2_b32 v[26:27], v12 offset0:148 offset1:181
	s_waitcnt lgkmcnt(0)
	v_cvt_pk_bf16_f32 v26, v26, v27
	ds_read2_b32 v[28:29], v12 offset0:214 offset1:247
	s_waitcnt lgkmcnt(0)
	v_cvt_pk_bf16_f32 v27, v28, v29
	v_or_b32_e32 v28, s20, v14
	v_mul_u32_u24_e32 v28, 0x1600, v28
	v_lshlrev_b32_e32 v28, 1, v28
	v_mov_b32_e32 v29, v1
	v_lshl_add_u64 v[28:29], v[6:7], 0, v[28:29]
	global_store_dwordx4 v[28:29], v[24:27], off nt
	ds_read2_b32 v[24:25], v12 offset0:24 offset1:57
	s_waitcnt lgkmcnt(0)
	v_cvt_pk_bf16_f32 v24, v24, v25
	ds_read2_b32 v[26:27], v12 offset0:90 offset1:123
	s_waitcnt lgkmcnt(0)
	v_cvt_pk_bf16_f32 v25, v26, v27
	ds_read2_b32 v[26:27], v12 offset0:156 offset1:189
	s_waitcnt lgkmcnt(0)
	v_cvt_pk_bf16_f32 v26, v26, v27
	ds_read2_b32 v[28:29], v12 offset0:222 offset1:255
	s_waitcnt lgkmcnt(0)
	v_cvt_pk_bf16_f32 v27, v28, v29
	v_or_b32_e32 v28, s20, v15
	v_mul_u32_u24_e32 v28, 0x1600, v28
	v_lshlrev_b32_e32 v28, 1, v28
	v_mov_b32_e32 v29, v1
	v_lshl_add_u64 v[6:7], v[6:7], 0, v[28:29]
	global_store_dwordx4 v[6:7], v[24:27], off nt
	s_waitcnt lgkmcnt(0)
.LBB0_607:
	s_andn2_b64 vcc, exec, s[16:17]
	s_cbranch_vccnz .LBB0_604
	s_load_dwordx2 s[88:89], s[8:9], 0x88
	s_mul_hi_i32 s14, s86, 0x2e8ba2e9
	s_lshr_b32 s16, s14, 31
	s_ashr_i32 s14, s14, 5
	s_add_i32 s14, s14, s16
	s_lshl_b32 s20, s14, 6
	s_mul_i32 s16, s14, 0xffffea00
	s_add_i32 s16, s5, s16
	v_or_b32_e32 v24, s20, v10
	s_waitcnt lgkmcnt(0)
	v_mov_b64_e32 v[6:7], s[88:89]
	v_mad_i64_i32 v[6:7], s[88:89], v24, s56, v[6:7]
	s_ashr_i32 s17, s16, 31
	v_lshl_add_u64 v[6:7], s[16:17], 2, v[6:7]
	v_lshl_add_u64 v[6:7], v[6:7], 0, v[0:1]
	v_add_co_u32_e32 v24, vcc, s57, v6
	global_load_dword v26, v[6:7], off nt
	s_nop 0
	v_addc_co_u32_e32 v25, vcc, 0, v7, vcc
	global_load_dword v27, v[24:25], off nt
	v_add_co_u32_e32 v24, vcc, s58, v6
	s_mulk_i32 s14, 0xd400
	s_nop 0
	v_addc_co_u32_e32 v25, vcc, 0, v7, vcc
	global_load_dword v28, v[24:25], off nt
	v_add_co_u32_e32 v24, vcc, s59, v6
	s_add_i32 s14, s7, s14
	s_nop 0
	v_addc_co_u32_e32 v25, vcc, 0, v7, vcc
	global_load_dword v29, v[24:25], off nt
	v_add_co_u32_e32 v24, vcc, s35, v6
	s_and_b32 s14, s14, 0xffffff00
	s_nop 0
	v_addc_co_u32_e32 v25, vcc, 0, v7, vcc
	global_load_dword v30, v[24:25], off nt
	v_add_co_u32_e32 v24, vcc, s60, v6
	s_and_b32 s16, s16, 0x60
	s_nop 0
	v_addc_co_u32_e32 v25, vcc, 0, v7, vcc
	global_load_dword v31, v[24:25], off nt
	v_add_co_u32_e32 v24, vcc, s61, v6
	s_or_b32 s14, s14, s16
	s_nop 0
	v_addc_co_u32_e32 v25, vcc, 0, v7, vcc
	global_load_dword v32, v[24:25], off nt
	v_add_co_u32_e32 v24, vcc, s62, v6
	s_bitset1_b32 s14, 7
	s_nop 0
	v_addc_co_u32_e32 v25, vcc, 0, v7, vcc
	global_load_dword v33, v[24:25], off nt
	v_add_co_u32_e32 v24, vcc, s46, v6
	s_ashr_i32 s21, s20, 31
	s_nop 0
	v_addc_co_u32_e32 v25, vcc, 0, v7, vcc
	global_load_dword v34, v[24:25], off nt
	v_add_co_u32_e32 v24, vcc, s63, v6
	s_nop 1
	v_addc_co_u32_e32 v25, vcc, 0, v7, vcc
	global_load_dword v35, v[24:25], off nt
	v_add_co_u32_e32 v24, vcc, s64, v6
	s_nop 1
	v_addc_co_u32_e32 v25, vcc, 0, v7, vcc
	global_load_dword v36, v[24:25], off nt
	v_add_co_u32_e32 v24, vcc, s65, v6
	s_nop 1
	v_addc_co_u32_e32 v25, vcc, 0, v7, vcc
	global_load_dword v37, v[24:25], off nt
	v_add_co_u32_e32 v24, vcc, s66, v6
	s_nop 1
	v_addc_co_u32_e32 v25, vcc, 0, v7, vcc
	global_load_dword v38, v[24:25], off nt
	v_add_co_u32_e32 v24, vcc, s67, v6
	s_nop 1
	v_addc_co_u32_e32 v25, vcc, 0, v7, vcc
	global_load_dword v39, v[24:25], off nt
	v_add_co_u32_e32 v24, vcc, s68, v6
	s_nop 1
	v_addc_co_u32_e32 v25, vcc, 0, v7, vcc
	global_load_dword v40, v[24:25], off nt
	v_add_co_u32_e32 v24, vcc, s69, v6
	s_nop 1
	v_addc_co_u32_e32 v25, vcc, 0, v7, vcc
	global_load_dword v41, v[24:25], off nt
	v_add_co_u32_e32 v24, vcc, s70, v6
	s_nop 1
	v_addc_co_u32_e32 v25, vcc, 0, v7, vcc
	global_load_dword v42, v[24:25], off nt
	v_add_co_u32_e32 v24, vcc, s71, v6
	s_nop 1
	v_addc_co_u32_e32 v25, vcc, 0, v7, vcc
; #define LAS __attribute__((address_space(3)))
; __device__ __forceinline__ unsigned pk2(float lo, float hi) { unsigned r; asm volatile("v_cvt_pk_bf16_f32 %0, %1, %2" : "=v"(r) : "v"(lo), "v"(hi)); return r; }
; __device__ __forceinline__ void p0_transpose_item(const float* W, int K, int N, bf16_t* WT, int mode, LAS float* scr, int item, int lane) {
;     ...
;     for (int i = 0; i < 32; ++i) v[i] = __builtin_nontemporal_load(wp + (size_t)(2 * i) * N);
; #pragma unroll
;     for (int i = 0; i < 32; ++i) scr[(2 * i + (lane >> 5)) * 33 + (lane & 31)] = v[i];
;     asm volatile("s_waitcnt lgkmcnt(0)" ::: "memory");
;     const int c = lane & 7;
; #pragma unroll
;     for (int j = 0; j < 4; ++j) { const int n = (lane >> 3) + 8 * j; const LAS float* s = scr + (8 * c) * 33 + n;
;         u32x4 o; o.x = pk2(s[0 * 33], s[1 * 33]); o.y = pk2(s[2 * 33], s[3 * 33]); o.z = pk2(s[4 * 33], s[5 * 33]); o.w = pk2(s[6 * 33], s[7 * 33]);
;         const int nn = n0 + n; const int drow = mode == 0 ? nn : ((nn >> 7) << 8) + (nn & 127) + (mode == 2 ? 128 : 0);
;         *(u32x4*)(WT + (size_t)drow * K + k0 + 8 * c) = o; }
	global_load_dword v43, v[24:25], off nt
	v_add_co_u32_e32 v24, vcc, s72, v6
	s_nop 1
	v_addc_co_u32_e32 v25, vcc, 0, v7, vcc
	global_load_dword v44, v[24:25], off nt
	v_add_co_u32_e32 v24, vcc, s73, v6
	s_nop 1
	v_addc_co_u32_e32 v25, vcc, 0, v7, vcc
	global_load_dword v45, v[24:25], off nt
	v_add_co_u32_e32 v24, vcc, s74, v6
	s_nop 1
	v_addc_co_u32_e32 v25, vcc, 0, v7, vcc
	global_load_dword v46, v[24:25], off nt
	v_add_co_u32_e32 v24, vcc, s75, v6
	s_nop 1
	v_addc_co_u32_e32 v25, vcc, 0, v7, vcc
	global_load_dword v47, v[24:25], off nt
	v_add_co_u32_e32 v24, vcc, s76, v6
	s_nop 1
	v_addc_co_u32_e32 v25, vcc, 0, v7, vcc
	global_load_dword v48, v[24:25], off nt
	v_add_co_u32_e32 v24, vcc, s77, v6
	s_nop 1
	v_addc_co_u32_e32 v25, vcc, 0, v7, vcc
	global_load_dword v49, v[24:25], off nt
	v_add_co_u32_e32 v24, vcc, s78, v6
	s_nop 1
	v_addc_co_u32_e32 v25, vcc, 0, v7, vcc
	global_load_dword v50, v[24:25], off nt
	v_add_co_u32_e32 v24, vcc, s79, v6
	s_nop 1
	v_addc_co_u32_e32 v25, vcc, 0, v7, vcc
	global_load_dword v51, v[24:25], off nt
	v_add_co_u32_e32 v24, vcc, s80, v6
	s_nop 1
	v_addc_co_u32_e32 v25, vcc, 0, v7, vcc
	global_load_dword v52, v[24:25], off nt
	v_add_co_u32_e32 v24, vcc, s81, v6
	s_nop 1
	v_addc_co_u32_e32 v25, vcc, 0, v7, vcc
	global_load_dword v53, v[24:25], off nt
	v_add_co_u32_e32 v24, vcc, s82, v6
	s_nop 1
	v_addc_co_u32_e32 v25, vcc, 0, v7, vcc
	global_load_dword v54, v[24:25], off nt
	v_add_co_u32_e32 v24, vcc, s83, v6
	s_nop 1
	v_addc_co_u32_e32 v25, vcc, 0, v7, vcc
	global_load_dword v55, v[24:25], off nt
	v_add_co_u32_e32 v24, vcc, s84, v6
	s_nop 1
	v_addc_co_u32_e32 v25, vcc, 0, v7, vcc
	v_add_co_u32_e32 v6, vcc, s85, v6
	global_load_dword v24, v[24:25], off nt
	s_nop 0
	v_addc_co_u32_e32 v7, vcc, 0, v7, vcc
	global_load_dword v6, v[6:7], off nt
	s_waitcnt vmcnt(30)
	ds_write2_b32 v16, v26, v27 offset1:66
	s_waitcnt vmcnt(28)
	ds_write2_b32 v16, v28, v29 offset0:132 offset1:198
	s_waitcnt vmcnt(26)
	ds_write2_b32 v17, v30, v31 offset0:8 offset1:74
	s_waitcnt vmcnt(24)
	ds_write2_b32 v17, v32, v33 offset0:140 offset1:206
	s_waitcnt vmcnt(22)
	ds_write2_b32 v18, v34, v35 offset0:16 offset1:82
	s_waitcnt vmcnt(20)
	ds_write2_b32 v18, v36, v37 offset0:148 offset1:214
	s_waitcnt vmcnt(18)
	ds_write2_b32 v19, v38, v39 offset0:24 offset1:90
	s_waitcnt vmcnt(16)
	ds_write2_b32 v19, v40, v41 offset0:156 offset1:222
	s_waitcnt vmcnt(14)
	ds_write2_b32 v20, v42, v43 offset0:32 offset1:98
	s_waitcnt vmcnt(12)
	ds_write2_b32 v20, v44, v45 offset0:164 offset1:230
	s_waitcnt vmcnt(10)
	ds_write2_b32 v21, v46, v47 offset0:40 offset1:106
	s_waitcnt vmcnt(8)
	ds_write2_b32 v21, v48, v49 offset0:172 offset1:238
	s_waitcnt vmcnt(6)
	ds_write2_b32 v22, v50, v51 offset0:48 offset1:114
	s_waitcnt vmcnt(4)
	ds_write2_b32 v22, v52, v53 offset0:180 offset1:246
	s_waitcnt vmcnt(2)
	ds_write2_b32 v23, v54, v55 offset0:56 offset1:122
	s_waitcnt vmcnt(0)
	ds_write2_b32 v23, v24, v6 offset0:188 offset1:254
	s_waitcnt lgkmcnt(0)
	ds_read2_b32 v[24:25], v12 offset1:33
	s_waitcnt lgkmcnt(0)
	v_cvt_pk_bf16_f32 v24, v24, v25
	ds_read2_b32 v[26:27], v12 offset0:66 offset1:99
	s_waitcnt lgkmcnt(0)
	v_cvt_pk_bf16_f32 v25, v26, v27
	ds_read2_b32 v[26:27], v12 offset0:132 offset1:165
	s_waitcnt lgkmcnt(0)
	v_cvt_pk_bf16_f32 v26, v26, v27
	ds_read2_b32 v[28:29], v12 offset0:198 offset1:231
	s_waitcnt lgkmcnt(0)
	v_cvt_pk_bf16_f32 v27, v28, v29
	v_or_b32_e32 v28, s14, v11
	v_ashrrev_i32_e32 v29, 31, v28
	v_lshl_add_u64 v[6:7], s[20:21], 1, v[4:5]
	v_lshlrev_b64 v[28:29], 12, v[28:29]
	v_lshl_add_u64 v[28:29], v[6:7], 0, v[28:29]
	global_store_dwordx4 v[28:29], v[24:27], off nt
	ds_read2_b32 v[24:25], v12 offset0:8 offset1:41
	s_waitcnt lgkmcnt(0)
	v_cvt_pk_bf16_f32 v24, v24, v25
	ds_read2_b32 v[26:27], v12 offset0:74 offset1:107
	s_waitcnt lgkmcnt(0)
	v_cvt_pk_bf16_f32 v25, v26, v27
	ds_read2_b32 v[26:27], v12 offset0:140 offset1:173
	s_waitcnt lgkmcnt(0)
	v_cvt_pk_bf16_f32 v26, v26, v27
	ds_read2_b32 v[28:29], v12 offset0:206 offset1:239
	s_waitcnt lgkmcnt(0)
	v_cvt_pk_bf16_f32 v27, v28, v29
	v_or_b32_e32 v28, s14, v13
	v_ashrrev_i32_e32 v29, 31, v28
	v_lshlrev_b64 v[28:29], 12, v[28:29]
	v_lshl_add_u64 v[28:29], v[6:7], 0, v[28:29]
	global_store_dwordx4 v[28:29], v[24:27], off nt
	ds_read2_b32 v[24:25], v12 offset0:16 offset1:49
	s_waitcnt lgkmcnt(0)
	v_cvt_pk_bf16_f32 v24, v24, v25
	ds_read2_b32 v[26:27], v12 offset0:82 offset1:115
	s_waitcnt lgkmcnt(0)
	v_cvt_pk_bf16_f32 v25, v26, v27
	ds_read2_b32 v[26:27], v12 offset0:148 offset1:181
	s_waitcnt lgkmcnt(0)
	v_cvt_pk_bf16_f32 v26, v26, v27
	ds_read2_b32 v[28:29], v12 offset0:214 offset1:247
	s_waitcnt lgkmcnt(0)
	v_cvt_pk_bf16_f32 v27, v28, v29
	v_or_b32_e32 v28, s14, v14
	v_ashrrev_i32_e32 v29, 31, v28
	v_lshlrev_b64 v[28:29], 12, v[28:29]
	v_lshl_add_u64 v[28:29], v[6:7], 0, v[28:29]
	global_store_dwordx4 v[28:29], v[24:27], off nt
	ds_read2_b32 v[24:25], v12 offset0:24 offset1:57
	s_waitcnt lgkmcnt(0)
	v_cvt_pk_bf16_f32 v24, v24, v25
	ds_read2_b32 v[26:27], v12 offset0:90 offset1:123
	s_waitcnt lgkmcnt(0)
	v_cvt_pk_bf16_f32 v25, v26, v27
	ds_read2_b32 v[26:27], v12 offset0:156 offset1:189
	s_waitcnt lgkmcnt(0)
	v_cvt_pk_bf16_f32 v26, v26, v27
	ds_read2_b32 v[28:29], v12 offset0:222 offset1:255
	s_waitcnt lgkmcnt(0)
	v_cvt_pk_bf16_f32 v27, v28, v29
	v_or_b32_e32 v28, s14, v15
	v_ashrrev_i32_e32 v29, 31, v28
	v_lshlrev_b64 v[28:29], 12, v[28:29]
	v_lshl_add_u64 v[6:7], v[6:7], 0, v[28:29]
	global_store_dwordx4 v[6:7], v[24:27], off nt
	s_waitcnt lgkmcnt(0)
	s_branch .LBB0_604

; #define LAS __attribute__((address_space(3)))
; __device__ __forceinline__ void p0_transpose_item(const float* W, int K, int N, bf16_t* WT, int mode, LAS float* scr, int item, int lane) {
;     const int nblk = N / 32, kb = item / nblk, nb = item % nblk, k0 = 64 * kb, n0 = 32 * nb;
;     float v[32];
;     const float* wp = W + (size_t)(k0 + (lane >> 5)) * N + n0 + (lane & 31);
; #pragma unroll
;     for (int i = 0; i < 32; ++i) v[i] = __builtin_nontemporal_load(wp + (size_t)(2 * i) * N);
; #pragma unroll
;     for (int i = 0; i < 32; ++i) scr[(2 * i + (lane >> 5)) * 33 + (lane & 31)] = v[i];
.LBB0_614:
	s_cmpk_gt_i32 s4, 0x15ff
	s_mov_b64 s[10:11], -1
	s_cbranch_scc0 .LBB0_616
	s_load_dwordx2 s[82:83], s[8:9], 0x90
	s_and_b32 s10, s4, 0x7fffffc0
	s_addk_i32 s10, 0xea00
	v_or_b32_e32 v20, s10, v6
	v_mov_b32_e32 v21, v1
	s_and_b32 s12, s3, 0x7e0
	v_lshlrev_b64 v[20:21], 13, v[20:21]
	s_waitcnt lgkmcnt(0)
	v_lshl_add_u64 v[20:21], s[82:83], 0, v[20:21]
	s_lshl_b32 s14, s12, 2
	v_lshl_add_u64 v[20:21], v[20:21], 0, s[14:15]
	v_lshl_add_u64 v[20:21], v[20:21], 0, v[0:1]
	v_add_co_u32_e32 v22, vcc, s6, v20
	s_mov_b32 s11, s15
	s_nop 0
	v_addc_co_u32_e32 v23, vcc, 0, v21, vcc
	v_add_co_u32_e32 v24, vcc, s7, v20
	s_nop 1
	v_addc_co_u32_e32 v25, vcc, 0, v21, vcc
	v_add_co_u32_e32 v26, vcc, s16, v20
	s_nop 1
	v_addc_co_u32_e32 v27, vcc, 0, v21, vcc
	v_add_co_u32_e32 v28, vcc, s17, v20
	s_nop 1
	v_addc_co_u32_e32 v29, vcc, 0, v21, vcc
	v_add_co_u32_e32 v30, vcc, s18, v20
	s_nop 1
	v_addc_co_u32_e32 v31, vcc, 0, v21, vcc
	v_add_co_u32_e32 v32, vcc, s19, v20
	s_nop 1
	v_addc_co_u32_e32 v33, vcc, 0, v21, vcc
	v_add_co_u32_e32 v34, vcc, s20, v20
	s_nop 1
	v_addc_co_u32_e32 v35, vcc, 0, v21, vcc
	global_load_dword v38, v[20:21], off nt
	global_load_dword v39, v[22:23], off nt
	global_load_dword v40, v[24:25], off nt
	global_load_dword v41, v[26:27], off nt
	global_load_dword v42, v[28:29], off nt
	global_load_dword v43, v[30:31], off nt
	global_load_dword v44, v[32:33], off nt
	global_load_dword v45, v[34:35], off nt
	v_add_co_u32_e32 v22, vcc, s21, v20
	s_nop 1
	v_addc_co_u32_e32 v23, vcc, 0, v21, vcc
	v_add_co_u32_e32 v24, vcc, s22, v20
	s_nop 1
	v_addc_co_u32_e32 v25, vcc, 0, v21, vcc
	v_add_co_u32_e32 v26, vcc, s23, v20
	s_nop 1
	v_addc_co_u32_e32 v27, vcc, 0, v21, vcc
	v_add_co_u32_e32 v28, vcc, s25, v20
	s_nop 1
	v_addc_co_u32_e32 v29, vcc, 0, v21, vcc
	v_add_co_u32_e32 v30, vcc, s26, v20
	s_nop 1
	v_addc_co_u32_e32 v31, vcc, 0, v21, vcc
	v_add_co_u32_e32 v32, vcc, s27, v20
	s_nop 1
	v_addc_co_u32_e32 v33, vcc, 0, v21, vcc
	v_add_co_u32_e32 v34, vcc, s33, v20
	s_nop 1
	v_addc_co_u32_e32 v35, vcc, 0, v21, vcc
	v_add_co_u32_e32 v36, vcc, s34, v20
	s_nop 1
	v_addc_co_u32_e32 v37, vcc, 0, v21, vcc
	global_load_dword v46, v[22:23], off nt
	global_load_dword v47, v[24:25], off nt
	global_load_dword v48, v[26:27], off nt
	global_load_dword v49, v[28:29], off nt
	global_load_dword v50, v[30:31], off nt
	global_load_dword v51, v[32:33], off nt
	global_load_dword v52, v[34:35], off nt
	global_load_dword v53, v[36:37], off nt
	v_add_co_u32_e32 v22, vcc, s35, v20
	s_nop 1
	v_addc_co_u32_e32 v23, vcc, 0, v21, vcc
	v_add_co_u32_e32 v24, vcc, s36, v20
	s_nop 1
	v_addc_co_u32_e32 v25, vcc, 0, v21, vcc
	v_add_co_u32_e32 v26, vcc, s37, v20
	s_nop 1
	v_addc_co_u32_e32 v27, vcc, 0, v21, vcc
	v_add_co_u32_e32 v28, vcc, s38, v20
	s_nop 1
	v_addc_co_u32_e32 v29, vcc, 0, v21, vcc
	v_add_co_u32_e32 v30, vcc, s39, v20
	s_nop 1
	v_addc_co_u32_e32 v31, vcc, 0, v21, vcc
	v_add_co_u32_e32 v32, vcc, s40, v20
	s_nop 1
	v_addc_co_u32_e32 v33, vcc, 0, v21, vcc
	v_add_co_u32_e32 v34, vcc, s41, v20
	s_nop 1
	v_addc_co_u32_e32 v35, vcc, 0, v21, vcc
	v_add_co_u32_e32 v36, vcc, s42, v20
	s_nop 1
	v_addc_co_u32_e32 v37, vcc, 0, v21, vcc
	global_load_dword v54, v[22:23], off nt
	global_load_dword v55, v[24:25], off nt
	global_load_dword v56, v[26:27], off nt
	global_load_dword v57, v[28:29], off nt
	global_load_dword v58, v[30:31], off nt
	global_load_dword v59, v[32:33], off nt
	global_load_dword v60, v[34:35], off nt
	s_nop 0
	global_load_dword v36, v[36:37], off nt
	v_add_co_u32_e32 v22, vcc, s43, v20
	s_nop 1
	v_addc_co_u32_e32 v23, vcc, 0, v21, vcc
	v_add_co_u32_e32 v24, vcc, s44, v20
	s_nop 1
	v_addc_co_u32_e32 v25, vcc, 0, v21, vcc
	v_add_co_u32_e32 v26, vcc, s45, v20
	s_nop 1
	v_addc_co_u32_e32 v27, vcc, 0, v21, vcc
	v_add_co_u32_e32 v28, vcc, s46, v20
	s_nop 1
	v_addc_co_u32_e32 v29, vcc, 0, v21, vcc
	v_add_co_u32_e32 v30, vcc, s47, v20
	s_nop 1
	v_addc_co_u32_e32 v31, vcc, 0, v21, vcc
	v_add_co_u32_e32 v32, vcc, s48, v20
	s_nop 1
	v_addc_co_u32_e32 v33, vcc, 0, v21, vcc
	v_add_co_u32_e32 v34, vcc, s49, v20
	s_nop 1
	v_addc_co_u32_e32 v35, vcc, 0, v21, vcc
	v_add_co_u32_e32 v20, vcc, s50, v20
	s_nop 1
	v_addc_co_u32_e32 v21, vcc, 0, v21, vcc
	global_load_dword v22, v[22:23], off nt
	s_nop 0
	global_load_dword v23, v[24:25], off nt
	s_nop 0
	global_load_dword v24, v[26:27], off nt
	global_load_dword v25, v[28:29], off nt
	s_nop 0
	global_load_dword v26, v[30:31], off nt
	global_load_dword v27, v[32:33], off nt
	global_load_dword v28, v[34:35], off nt
	s_nop 0
	global_load_dword v20, v[20:21], off nt
	s_waitcnt vmcnt(30)
	ds_write2_b32 v12, v38, v39 offset1:66
	s_waitcnt vmcnt(28)
	ds_write2_b32 v12, v40, v41 offset0:132 offset1:198
	s_waitcnt vmcnt(26)
	ds_write2_b32 v13, v42, v43 offset0:8 offset1:74
	s_waitcnt vmcnt(24)
	ds_write2_b32 v13, v44, v45 offset0:140 offset1:206
	s_waitcnt vmcnt(22)
	ds_write2_b32 v14, v46, v47 offset0:16 offset1:82
	s_waitcnt vmcnt(20)
	ds_write2_b32 v14, v48, v49 offset0:148 offset1:214
	s_waitcnt vmcnt(18)
	ds_write2_b32 v15, v50, v51 offset0:24 offset1:90
	s_waitcnt vmcnt(16)
	ds_write2_b32 v15, v52, v53 offset0:156 offset1:222
	s_waitcnt vmcnt(14)
	ds_write2_b32 v16, v54, v55 offset0:32 offset1:98
	s_waitcnt vmcnt(12)
	ds_write2_b32 v16, v56, v57 offset0:164 offset1:230
	s_waitcnt vmcnt(10)
	ds_write2_b32 v17, v58, v59 offset0:40 offset1:106
	s_waitcnt vmcnt(8)
	ds_write2_b32 v17, v60, v36 offset0:172 offset1:238
	s_waitcnt vmcnt(6)
	ds_write2_b32 v18, v22, v23 offset0:48 offset1:114
	s_waitcnt vmcnt(4)
	ds_write2_b32 v18, v24, v25 offset0:180 offset1:246
	s_waitcnt vmcnt(2)
	ds_write2_b32 v19, v26, v27 offset0:56 offset1:122
	s_waitcnt vmcnt(0)
; #define LAS __attribute__((address_space(3)))
; __device__ __forceinline__ unsigned pk2(float lo, float hi) { unsigned r; asm volatile("v_cvt_pk_bf16_f32 %0, %1, %2" : "=v"(r) : "v"(lo), "v"(hi)); return r; }
; __device__ __forceinline__ void p0_transpose_item(const float* W, int K, int N, bf16_t* WT, int mode, LAS float* scr, int item, int lane) {
;     ...
;     for (int i = 0; i < 32; ++i) scr[(2 * i + (lane >> 5)) * 33 + (lane & 31)] = v[i];
;     asm volatile("s_waitcnt lgkmcnt(0)" ::: "memory");
;     const int c = lane & 7;
; #pragma unroll
;     for (int j = 0; j < 4; ++j) { const int n = (lane >> 3) + 8 * j; const LAS float* s = scr + (8 * c) * 33 + n;
;         u32x4 o; o.x = pk2(s[0 * 33], s[1 * 33]); o.y = pk2(s[2 * 33], s[3 * 33]); o.z = pk2(s[4 * 33], s[5 * 33]); o.w = pk2(s[6 * 33], s[7 * 33]);
;         const int nn = n0 + n; const int drow = mode == 0 ? nn : ((nn >> 7) << 8) + (nn & 127) + (mode == 2 ? 128 : 0);
;         *(u32x4*)(WT + (size_t)drow * K + k0 + 8 * c) = o; }
	ds_write2_b32 v19, v28, v20 offset0:188 offset1:254
	s_waitcnt lgkmcnt(0)
	ds_read2_b32 v[20:21], v8 offset1:33
	s_waitcnt lgkmcnt(0)
	v_cvt_pk_bf16_f32 v20, v20, v21
	ds_read2_b32 v[22:23], v8 offset0:66 offset1:99
	s_waitcnt lgkmcnt(0)
	v_cvt_pk_bf16_f32 v21, v22, v23
	ds_read2_b32 v[22:23], v8 offset0:132 offset1:165
	s_waitcnt lgkmcnt(0)
	v_cvt_pk_bf16_f32 v22, v22, v23
	ds_read2_b32 v[24:25], v8 offset0:198 offset1:231
	s_waitcnt lgkmcnt(0)
	v_cvt_pk_bf16_f32 v23, v24, v25
	v_or_b32_e32 v24, s12, v7
	v_mul_u32_u24_e32 v28, 0x1600, v24
	v_lshl_add_u64 v[26:27], s[10:11], 1, v[2:3]
	v_lshlrev_b32_e32 v28, 1, v28
	v_mov_b32_e32 v29, v1
	v_lshl_add_u64 v[28:29], v[26:27], 0, v[28:29]
	ds_read2_b32 v[24:25], v8 offset0:8 offset1:41
	global_store_dwordx4 v[28:29], v[20:23], off nt
	v_mov_b32_e32 v29, v1
	s_mov_b64 s[10:11], 0
	s_waitcnt lgkmcnt(0)
	v_cvt_pk_bf16_f32 v20, v24, v25
	ds_read2_b32 v[22:23], v8 offset0:74 offset1:107
	s_waitcnt lgkmcnt(0)
	v_cvt_pk_bf16_f32 v21, v22, v23
	ds_read2_b32 v[22:23], v8 offset0:140 offset1:173
	s_waitcnt lgkmcnt(0)
	v_cvt_pk_bf16_f32 v22, v22, v23
	ds_read2_b32 v[24:25], v8 offset0:206 offset1:239
	s_waitcnt lgkmcnt(0)
	v_cvt_pk_bf16_f32 v23, v24, v25
	v_or_b32_e32 v24, s12, v9
	v_mul_u32_u24_e32 v28, 0x1600, v24
	v_lshlrev_b32_e32 v28, 1, v28
	v_lshl_add_u64 v[28:29], v[26:27], 0, v[28:29]
	ds_read2_b32 v[24:25], v8 offset0:16 offset1:49
	global_store_dwordx4 v[28:29], v[20:23], off nt
	v_mov_b32_e32 v29, v1
	s_waitcnt lgkmcnt(0)
	v_cvt_pk_bf16_f32 v20, v24, v25
	ds_read2_b32 v[22:23], v8 offset0:82 offset1:115
	s_waitcnt lgkmcnt(0)
	v_cvt_pk_bf16_f32 v21, v22, v23
	ds_read2_b32 v[22:23], v8 offset0:148 offset1:181
	s_waitcnt lgkmcnt(0)
	v_cvt_pk_bf16_f32 v22, v22, v23
	ds_read2_b32 v[24:25], v8 offset0:214 offset1:247
	s_waitcnt lgkmcnt(0)
	v_cvt_pk_bf16_f32 v23, v24, v25
	v_or_b32_e32 v24, s12, v10
	v_mul_u32_u24_e32 v28, 0x1600, v24
	v_lshlrev_b32_e32 v28, 1, v28
	v_lshl_add_u64 v[28:29], v[26:27], 0, v[28:29]
	ds_read2_b32 v[24:25], v8 offset0:24 offset1:57
	global_store_dwordx4 v[28:29], v[20:23], off nt
	s_waitcnt lgkmcnt(0)
	s_nop 0
	v_cvt_pk_bf16_f32 v20, v24, v25
	ds_read2_b32 v[22:23], v8 offset0:90 offset1:123
	s_waitcnt lgkmcnt(0)
	v_cvt_pk_bf16_f32 v21, v22, v23
	ds_read2_b32 v[22:23], v8 offset0:156 offset1:189
	s_waitcnt lgkmcnt(0)
	v_cvt_pk_bf16_f32 v22, v22, v23
	ds_read2_b32 v[24:25], v8 offset0:222 offset1:255
	s_waitcnt lgkmcnt(0)
	v_cvt_pk_bf16_f32 v23, v24, v25
	v_or_b32_e32 v24, s12, v11
	v_mul_u32_u24_e32 v24, 0x1600, v24
	v_lshlrev_b32_e32 v24, 1, v24
	v_mov_b32_e32 v25, v1
	v_lshl_add_u64 v[24:25], v[26:27], 0, v[24:25]
	global_store_dwordx4 v[24:25], v[20:23], off nt
	s_waitcnt lgkmcnt(0)
.LBB0_616:
	s_andn2_b64 vcc, exec, s[10:11]
	s_cbranch_vccnz .LBB0_613
	s_load_dwordx2 s[82:83], s[8:9], 0x88
	s_mul_hi_i32 s10, s4, 0x2e8ba2e9
	s_lshr_b32 s11, s10, 31
	s_ashr_i32 s13, s10, 5
	s_add_i32 s13, s13, s11
	s_lshl_b32 s12, s13, 6
	s_mul_i32 s10, s13, 0xffffea00
	s_add_i32 s10, s3, s10
	v_or_b32_e32 v22, s12, v6
	s_waitcnt lgkmcnt(0)
	v_mov_b64_e32 v[20:21], s[82:83]
	v_mad_i64_i32 v[20:21], s[82:83], v22, s51, v[20:21]
	s_ashr_i32 s11, s10, 31
	v_lshl_add_u64 v[20:21], s[10:11], 2, v[20:21]
	v_lshl_add_u64 v[20:21], v[20:21], 0, v[0:1]
	v_add_co_u32_e32 v22, vcc, s52, v20
	s_mulk_i32 s13, 0xd400
	s_nop 0
	v_addc_co_u32_e32 v23, vcc, 0, v21, vcc
	v_add_co_u32_e32 v24, vcc, s53, v20
	s_add_i32 s11, s5, s13
	s_nop 0
	v_addc_co_u32_e32 v25, vcc, 0, v21, vcc
	v_add_co_u32_e32 v26, vcc, s54, v20
	s_and_b32 s11, s11, 0xffffff00
	s_nop 0
	v_addc_co_u32_e32 v27, vcc, 0, v21, vcc
	v_add_co_u32_e32 v28, vcc, s25, v20
	s_and_b32 s10, s10, 0x60
	s_nop 0
	v_addc_co_u32_e32 v29, vcc, 0, v21, vcc
	v_add_co_u32_e32 v30, vcc, s55, v20
	s_or_b32 s10, s11, s10
	s_nop 0
	v_addc_co_u32_e32 v31, vcc, 0, v21, vcc
	v_add_co_u32_e32 v32, vcc, s56, v20
	s_bitset1_b32 s10, 7
	s_nop 0
	v_addc_co_u32_e32 v33, vcc, 0, v21, vcc
	v_add_co_u32_e32 v34, vcc, s57, v20
	s_ashr_i32 s13, s12, 31
	s_nop 0
	v_addc_co_u32_e32 v35, vcc, 0, v21, vcc
	global_load_dword v38, v[20:21], off nt
	global_load_dword v39, v[22:23], off nt
	global_load_dword v40, v[24:25], off nt
	global_load_dword v41, v[26:27], off nt
	global_load_dword v42, v[28:29], off nt
	global_load_dword v43, v[30:31], off nt
	global_load_dword v44, v[32:33], off nt
	global_load_dword v45, v[34:35], off nt
	v_add_co_u32_e32 v22, vcc, s41, v20
	s_nop 1
	v_addc_co_u32_e32 v23, vcc, 0, v21, vcc
	v_add_co_u32_e32 v24, vcc, s58, v20
	s_nop 1
	v_addc_co_u32_e32 v25, vcc, 0, v21, vcc
	v_add_co_u32_e32 v26, vcc, s59, v20
	s_nop 1
	v_addc_co_u32_e32 v27, vcc, 0, v21, vcc
	v_add_co_u32_e32 v28, vcc, s60, v20
	s_nop 1
	v_addc_co_u32_e32 v29, vcc, 0, v21, vcc
	v_add_co_u32_e32 v30, vcc, s61, v20
	s_nop 1
	v_addc_co_u32_e32 v31, vcc, 0, v21, vcc
	v_add_co_u32_e32 v32, vcc, s62, v20
	s_nop 1
	v_addc_co_u32_e32 v33, vcc, 0, v21, vcc
	v_add_co_u32_e32 v34, vcc, s63, v20
	s_nop 1
	v_addc_co_u32_e32 v35, vcc, 0, v21, vcc
	v_add_co_u32_e32 v36, vcc, s64, v20
	s_nop 1
	v_addc_co_u32_e32 v37, vcc, 0, v21, vcc
	global_load_dword v46, v[22:23], off nt
	global_load_dword v47, v[24:25], off nt
	global_load_dword v48, v[26:27], off nt
	global_load_dword v49, v[28:29], off nt
	global_load_dword v50, v[30:31], off nt
	global_load_dword v51, v[32:33], off nt
	global_load_dword v52, v[34:35], off nt
	global_load_dword v53, v[36:37], off nt
	v_add_co_u32_e32 v22, vcc, s65, v20
	s_nop 1
	v_addc_co_u32_e32 v23, vcc, 0, v21, vcc
	v_add_co_u32_e32 v24, vcc, s66, v20
	s_nop 1
	v_addc_co_u32_e32 v25, vcc, 0, v21, vcc
	v_add_co_u32_e32 v26, vcc, s67, v20
	s_nop 1
; #define LAS __attribute__((address_space(3)))
; __device__ __forceinline__ unsigned pk2(float lo, float hi) { unsigned r; asm volatile("v_cvt_pk_bf16_f32 %0, %1, %2" : "=v"(r) : "v"(lo), "v"(hi)); return r; }
; __device__ __forceinline__ void p0_transpose_item(const float* W, int K, int N, bf16_t* WT, int mode, LAS float* scr, int item, int lane) {
;     ...
;     for (int i = 0; i < 32; ++i) v[i] = __builtin_nontemporal_load(wp + (size_t)(2 * i) * N);
; #pragma unroll
;     for (int i = 0; i < 32; ++i) scr[(2 * i + (lane >> 5)) * 33 + (lane & 31)] = v[i];
;     asm volatile("s_waitcnt lgkmcnt(0)" ::: "memory");
;     const int c = lane & 7;
; #pragma unroll
;     for (int j = 0; j < 4; ++j) { const int n = (lane >> 3) + 8 * j; const LAS float* s = scr + (8 * c) * 33 + n;
;         u32x4 o; o.x = pk2(s[0 * 33], s[1 * 33]); o.y = pk2(s[2 * 33], s[3 * 33]); o.z = pk2(s[4 * 33], s[5 * 33]); o.w = pk2(s[6 * 33], s[7 * 33]);
;         const int nn = n0 + n; const int drow = mode == 0 ? nn : ((nn >> 7) << 8) + (nn & 127) + (mode == 2 ? 128 : 0);
;         *(u32x4*)(WT + (size_t)drow * K + k0 + 8 * c) = o; }
	v_addc_co_u32_e32 v27, vcc, 0, v21, vcc
	v_add_co_u32_e32 v28, vcc, s68, v20
	s_nop 1
	v_addc_co_u32_e32 v29, vcc, 0, v21, vcc
	v_add_co_u32_e32 v30, vcc, s69, v20
	s_nop 1
	v_addc_co_u32_e32 v31, vcc, 0, v21, vcc
	v_add_co_u32_e32 v32, vcc, s70, v20
	s_nop 1
	v_addc_co_u32_e32 v33, vcc, 0, v21, vcc
	v_add_co_u32_e32 v34, vcc, s71, v20
	s_nop 1
	v_addc_co_u32_e32 v35, vcc, 0, v21, vcc
	v_add_co_u32_e32 v36, vcc, s72, v20
	s_nop 1
	v_addc_co_u32_e32 v37, vcc, 0, v21, vcc
	global_load_dword v54, v[22:23], off nt
	global_load_dword v55, v[24:25], off nt
	global_load_dword v56, v[26:27], off nt
	global_load_dword v57, v[28:29], off nt
	global_load_dword v58, v[30:31], off nt
	global_load_dword v59, v[32:33], off nt
	global_load_dword v60, v[34:35], off nt
	s_nop 0
	global_load_dword v36, v[36:37], off nt
	v_add_co_u32_e32 v22, vcc, s73, v20
	s_nop 1
	v_addc_co_u32_e32 v23, vcc, 0, v21, vcc
	v_add_co_u32_e32 v24, vcc, s74, v20
	s_nop 1
	v_addc_co_u32_e32 v25, vcc, 0, v21, vcc
	v_add_co_u32_e32 v26, vcc, s75, v20
	s_nop 1
	v_addc_co_u32_e32 v27, vcc, 0, v21, vcc
	v_add_co_u32_e32 v28, vcc, s76, v20
	s_nop 1
	v_addc_co_u32_e32 v29, vcc, 0, v21, vcc
	v_add_co_u32_e32 v30, vcc, s77, v20
	s_nop 1
	v_addc_co_u32_e32 v31, vcc, 0, v21, vcc
	v_add_co_u32_e32 v32, vcc, s78, v20
	s_nop 1
	v_addc_co_u32_e32 v33, vcc, 0, v21, vcc
	v_add_co_u32_e32 v34, vcc, s79, v20
	s_nop 1
	v_addc_co_u32_e32 v35, vcc, 0, v21, vcc
	v_add_co_u32_e32 v20, vcc, s80, v20
	s_nop 1
	v_addc_co_u32_e32 v21, vcc, 0, v21, vcc
	global_load_dword v22, v[22:23], off nt
	s_nop 0
	global_load_dword v23, v[24:25], off nt
	s_nop 0
	global_load_dword v24, v[26:27], off nt
	global_load_dword v25, v[28:29], off nt
	s_nop 0
	global_load_dword v26, v[30:31], off nt
	global_load_dword v27, v[32:33], off nt
	global_load_dword v28, v[34:35], off nt
	s_nop 0
	global_load_dword v20, v[20:21], off nt
	s_waitcnt vmcnt(30)
	ds_write2_b32 v12, v38, v39 offset1:66
	s_waitcnt vmcnt(28)
	ds_write2_b32 v12, v40, v41 offset0:132 offset1:198
	s_waitcnt vmcnt(26)
	ds_write2_b32 v13, v42, v43 offset0:8 offset1:74
	s_waitcnt vmcnt(24)
	ds_write2_b32 v13, v44, v45 offset0:140 offset1:206
	s_waitcnt vmcnt(22)
	ds_write2_b32 v14, v46, v47 offset0:16 offset1:82
	s_waitcnt vmcnt(20)
	ds_write2_b32 v14, v48, v49 offset0:148 offset1:214
	s_waitcnt vmcnt(18)
	ds_write2_b32 v15, v50, v51 offset0:24 offset1:90
	s_waitcnt vmcnt(16)
	ds_write2_b32 v15, v52, v53 offset0:156 offset1:222
	s_waitcnt vmcnt(14)
	ds_write2_b32 v16, v54, v55 offset0:32 offset1:98
	s_waitcnt vmcnt(12)
	ds_write2_b32 v16, v56, v57 offset0:164 offset1:230
	s_waitcnt vmcnt(10)
	ds_write2_b32 v17, v58, v59 offset0:40 offset1:106
	s_waitcnt vmcnt(8)
	ds_write2_b32 v17, v60, v36 offset0:172 offset1:238
	s_waitcnt vmcnt(6)
	ds_write2_b32 v18, v22, v23 offset0:48 offset1:114
	s_waitcnt vmcnt(4)
	ds_write2_b32 v18, v24, v25 offset0:180 offset1:246
	s_waitcnt vmcnt(2)
	ds_write2_b32 v19, v26, v27 offset0:56 offset1:122
	s_waitcnt vmcnt(0)
	ds_write2_b32 v19, v28, v20 offset0:188 offset1:254
	s_waitcnt lgkmcnt(0)
	ds_read2_b32 v[20:21], v8 offset1:33
	s_waitcnt lgkmcnt(0)
	v_cvt_pk_bf16_f32 v20, v20, v21
	ds_read2_b32 v[22:23], v8 offset0:66 offset1:99
	s_waitcnt lgkmcnt(0)
	v_cvt_pk_bf16_f32 v21, v22, v23
	ds_read2_b32 v[22:23], v8 offset0:132 offset1:165
	s_waitcnt lgkmcnt(0)
	v_cvt_pk_bf16_f32 v22, v22, v23
	ds_read2_b32 v[24:25], v8 offset0:198 offset1:231
	s_waitcnt lgkmcnt(0)
	v_cvt_pk_bf16_f32 v23, v24, v25
	v_or_b32_e32 v24, s10, v7
	v_ashrrev_i32_e32 v25, 31, v24
	v_lshl_add_u64 v[26:27], s[12:13], 1, v[4:5]
	v_lshlrev_b64 v[24:25], 12, v[24:25]
	v_lshl_add_u64 v[24:25], v[26:27], 0, v[24:25]
	ds_read2_b32 v[28:29], v8 offset0:8 offset1:41
	global_store_dwordx4 v[24:25], v[20:23], off nt
	s_waitcnt lgkmcnt(0)
	s_nop 0
	v_cvt_pk_bf16_f32 v20, v28, v29
	ds_read2_b32 v[22:23], v8 offset0:74 offset1:107
	s_waitcnt lgkmcnt(0)
	v_cvt_pk_bf16_f32 v21, v22, v23
	ds_read2_b32 v[22:23], v8 offset0:140 offset1:173
	s_waitcnt lgkmcnt(0)
	v_cvt_pk_bf16_f32 v22, v22, v23
	ds_read2_b32 v[24:25], v8 offset0:206 offset1:239
	s_waitcnt lgkmcnt(0)
	v_cvt_pk_bf16_f32 v23, v24, v25
	v_or_b32_e32 v24, s10, v9
	v_ashrrev_i32_e32 v25, 31, v24
	v_lshlrev_b64 v[24:25], 12, v[24:25]
	v_lshl_add_u64 v[24:25], v[26:27], 0, v[24:25]
	ds_read2_b32 v[28:29], v8 offset0:16 offset1:49
	global_store_dwordx4 v[24:25], v[20:23], off nt
	s_waitcnt lgkmcnt(0)
	s_nop 0
	v_cvt_pk_bf16_f32 v20, v28, v29
	ds_read2_b32 v[22:23], v8 offset0:82 offset1:115
	s_waitcnt lgkmcnt(0)
	v_cvt_pk_bf16_f32 v21, v22, v23
	ds_read2_b32 v[22:23], v8 offset0:148 offset1:181
	s_waitcnt lgkmcnt(0)
	v_cvt_pk_bf16_f32 v22, v22, v23
	ds_read2_b32 v[24:25], v8 offset0:214 offset1:247
	s_waitcnt lgkmcnt(0)
	v_cvt_pk_bf16_f32 v23, v24, v25
	v_or_b32_e32 v24, s10, v10
	v_ashrrev_i32_e32 v25, 31, v24
	v_lshlrev_b64 v[24:25], 12, v[24:25]
	v_lshl_add_u64 v[24:25], v[26:27], 0, v[24:25]
	ds_read2_b32 v[28:29], v8 offset0:24 offset1:57
	global_store_dwordx4 v[24:25], v[20:23], off nt
	s_waitcnt lgkmcnt(0)
	s_nop 0
	v_cvt_pk_bf16_f32 v20, v28, v29
	ds_read2_b32 v[22:23], v8 offset0:90 offset1:123
	s_waitcnt lgkmcnt(0)
	v_cvt_pk_bf16_f32 v21, v22, v23
	ds_read2_b32 v[22:23], v8 offset0:156 offset1:189
	s_waitcnt lgkmcnt(0)
	v_cvt_pk_bf16_f32 v22, v22, v23
	ds_read2_b32 v[24:25], v8 offset0:222 offset1:255
	s_waitcnt lgkmcnt(0)
	v_cvt_pk_bf16_f32 v23, v24, v25
	v_or_b32_e32 v24, s10, v11
	v_ashrrev_i32_e32 v25, 31, v24
	v_lshlrev_b64 v[24:25], 12, v[24:25]
	v_lshl_add_u64 v[24:25], v[26:27], 0, v[24:25]
	global_store_dwordx4 v[24:25], v[20:23], off nt
	s_waitcnt lgkmcnt(0)
	s_branch .LBB0_613
